# re-scheduled mixers: differential-attention items moved to the head of the NSA/GDN-output phase (reverse order), nsa_compress hidden loop rewritten with batched LDS reads
# speedup vs baseline: 1.1784x; 1.0080x over previous
; DI int tid_() { int t = __builtin_amdgcn_workitem_id_x(); asm volatile("" : "+v"(t)); return t; }
; DI unsigned xb_ld(unsigned* p) { return __hip_atomic_load(p, __ATOMIC_RELAXED, __HIP_MEMORY_SCOPE_AGENT); }
; DI unsigned xb_add(unsigned* p, unsigned v) { return __hip_atomic_fetch_add(p, v, __ATOMIC_RELAXED, __HIP_MEMORY_SCOPE_AGENT); }
; DI unsigned xb_xcc_id() { return (unsigned)__builtin_amdgcn_s_getreg((3 << 11) | 20) & 0xFu; }
; __global__ void __launch_bounds__(256, 2) mega(Params p, int ph0, int ph1, int coop) {
;   __shared__ __attribute__((aligned(16))) char smem[65536];
;     ...
;   run_phase(p, PHASE_ONLY, smem); return;
;     ...
;   XB xb; xb.x = xb_xcc_id(); xb.nloc = 1u; xb.nx = 1u;
;   unsigned* bar = (unsigned*)(p.ws + OFF_BAR);
;   if (coop && tid_() == 0) xb_add(bar + XB_XCNT(xb.x), 1u);
;   for (int ph = ph0; ph < ph1; ++ph) {
;     const Params& q = p;
;     run_phase(q, ph, smem);
;     ...
;     { const int sp = (ph - 1) % 12; const int l = (ph - 1) / 12;
;       if (ph > 0 && PROBE_DUP == 1 && (sp == 0 || sp == 9)) { cg::this_grid().sync(); run_phase(q, ph, smem); }
;       if (ph > 0 && PROBE_DUP == 2 && sp == 5) { cg::this_grid().sync(); m1_phase(q, l, smem, 32, 32); }
;       if (ph > 0 && PROBE_DUP == 3 && sp == 6) { cg::this_grid().sync(); m2_phase(q, l, smem, 48); }
;       if (ph > 0 && PROBE_DUP == 6 && sp == 6) { cg::this_grid().sync(); for (int it = blockIdx.x; it < 1024; it += gridDim.x) gdn_g3(q, l, it, smem); }
;       if (ph > 0 && PROBE_DUP == 7 && sp == 4) { cg::this_grid().sync(); for (int it = blockIdx.x; it < 2560; it += gridDim.x) vt_tile(q, it, smem); }
;       if (PROBE_DUP == 8 && ph < 20) { cg::this_grid().sync(); cg::this_grid().sync(); }
;       if (ph > 0 && PROBE_DUP == 4 && sp == 3) { cg::this_grid().sync(); run_phase(q, ph, smem); }
;       if (ph > 0 && PROBE_DUP == 5 && sp == 4) { cg::this_grid().sync(); for (int it = blockIdx.x; it < 2560 + 1024; it += gridDim.x) { if (it < 1024) gdn_g1(q, l, it, smem); else vt_tile(q, it - 1024, smem); } } }
;     ...
;     if (coop && ph + 1 < ph1) {
;       if (ph == 0) { cg::this_grid().sync();
;         unsigned mine = 0u, cnt = 0u;
;         for (unsigned j = 0; j < 16; ++j) { const unsigned c = xb_ld(bar + XB_XCNT(j)); cnt += c > 0u ? 1u : 0u; mine = (j == xb.x) ? c : mine; }
;         xb.nloc = mine > 0u ? mine : 1u; xb.nx = cnt > 0u ? cnt : 1u; }
.LBB0_6:
	s_mov_b32 s2, 0
	s_nop 3
	v_writelane_b32 v242, s2, 62
	s_load_dwordx8 s[8:15], s[0:1], 0xc0
	v_and_b32_e32 v170, 0x3ff, v0
	v_and_b32_e32 v0, 0x3fffffff, v0
	v_mbcnt_lo_u32_b32 v176, -1, 0
	v_mbcnt_hi_u32_b32 v177, -1, v176
	s_waitcnt lgkmcnt(0)
	v_writelane_b32 v245, s8, 12
	v_mov_b32_e32 v143, 0
	v_and_b32_e32 v178, 64, v177
	v_writelane_b32 v245, s9, 13
	v_writelane_b32 v245, s10, 14
	v_writelane_b32 v245, s11, 15
	v_writelane_b32 v245, s12, 16
	v_writelane_b32 v245, s13, 17
	v_writelane_b32 v245, s14, 18
	v_writelane_b32 v245, s15, 19
	s_load_dwordx16 s[36:51], s[0:1], 0x0
	s_load_dwordx16 s[8:23], s[0:1], 0x40
	v_mov_b32_e32 v141, 1
	v_mov_b32_e32 v186, 1
	v_mov_b32_e32 v171, 0x3727c5ac
	s_mov_b32 s33, 0xffff0000
	s_waitcnt lgkmcnt(0)
	v_writelane_b32 v245, s8, 20
	v_mov_b32_e32 v172, 0x3ecc95a3
	v_mov_b32_e32 v173, 0x358637bd
	v_writelane_b32 v245, s9, 21
	v_writelane_b32 v245, s10, 22
	v_writelane_b32 v245, s11, 23
	v_writelane_b32 v245, s12, 24
	v_writelane_b32 v245, s13, 25
	v_writelane_b32 v245, s14, 26
	v_writelane_b32 v245, s15, 27
	v_writelane_b32 v245, s16, 28
	v_writelane_b32 v245, s17, 29
	v_writelane_b32 v245, s18, 30
	v_writelane_b32 v245, s19, 31
	v_writelane_b32 v245, s20, 32
	v_writelane_b32 v245, s21, 33
	v_writelane_b32 v245, s22, 34
	v_writelane_b32 v245, s23, 35
	s_load_dwordx16 s[8:23], s[0:1], 0x80
	s_mov_b64 s[28:29], 0x240
	v_mov_b32_e32 v174, 0x3f4ccccd
	v_mov_b32_e32 v175, 0x3e91f4c4
	v_add_u32_e32 v179, 64, v178
	s_waitcnt lgkmcnt(0)
	v_writelane_b32 v245, s8, 36
	v_xor_b32_e32 v180, 32, v177
	v_xor_b32_e32 v181, 16, v177
	v_writelane_b32 v245, s9, 37
	v_writelane_b32 v245, s10, 38
	v_writelane_b32 v245, s11, 39
	v_writelane_b32 v245, s12, 40
	v_writelane_b32 v245, s13, 41
	v_writelane_b32 v245, s14, 42
	v_writelane_b32 v245, s15, 43
	v_writelane_b32 v245, s16, 44
	v_writelane_b32 v245, s17, 45
	v_writelane_b32 v245, s18, 46
	v_writelane_b32 v245, s19, 47
	v_writelane_b32 v245, s20, 48
	v_writelane_b32 v245, s21, 49
	v_writelane_b32 v245, s22, 50
	v_writelane_b32 v245, s23, 51
	s_load_dwordx8 s[8:15], s[0:1], 0xe0
	s_movk_i32 s17, 0x7fff
	s_movk_i32 s18, 0x5800
	s_mov_b32 s16, 0x3e000000
	s_waitcnt lgkmcnt(0)
	s_mov_b64 s[14:15], 0x200
	s_add_u32 s2, s10, 0x1900000
	s_addc_u32 s3, s11, 0
	v_writelane_b32 v245, s2, 52
	s_mov_b32 s19, 0xefa18f08
	v_xor_b32_e32 v182, 8, v177
	v_writelane_b32 v245, s3, 53
	s_add_u32 s2, s10, 0x3900000
	s_addc_u32 s3, s11, 0
	v_writelane_b32 v245, s2, 54
	v_xor_b32_e32 v183, 4, v177
	v_xor_b32_e32 v184, 2, v177
	v_writelane_b32 v245, s3, 55
	s_add_u32 s2, s10, 0xb00000
	s_addc_u32 s3, s11, 0
	v_writelane_b32 v245, s2, 56
	v_xor_b32_e32 v185, 1, v177
	v_mov_b32_e32 v187, 0x7f800000
	v_writelane_b32 v245, s3, 57
	s_add_u32 s2, s10, 0xe900000
	s_addc_u32 s3, s11, 0
	v_writelane_b32 v245, s2, 58
	v_mov_b32_e32 v144, 0x3f317218
	v_mov_b32_e32 v188, 0x4400
	v_writelane_b32 v245, s3, 59
	s_lshl_b32 s2, s24, 2
	s_add_u32 s0, s0, 0x100
	v_writelane_b32 v245, s2, 60
	s_addc_u32 s1, s1, 0
	v_writelane_b32 v245, s0, 61
	s_cmpk_lt_i32 s24, 0xc80
	s_mov_b32 s3, 0
	v_writelane_b32 v245, s1, 62
	s_cselect_b64 s[0:1], -1, 0
	v_writelane_b32 v245, s0, 63
	s_mov_b32 s25, s3
	v_readlane_b32 s4, v245, 0
	v_writelane_b32 v244, s1, 0
	s_add_u32 s0, s10, 0x1700000
	s_addc_u32 s1, s11, 0
	v_writelane_b32 v244, s0, 1
	v_readlane_b32 s5, v245, 1
	v_mov_b32_e32 v189, 0xf149f2ca
	v_writelane_b32 v244, s1, 2
	s_add_u32 s0, s10, 0x1080000
	s_addc_u32 s1, s11, 0
	v_writelane_b32 v244, s0, 3
	s_cmpk_lt_i32 s24, 0x840
	v_mov_b32_e32 v190, 0x461c4000
	v_writelane_b32 v244, s1, 4
	s_cselect_b64 s[0:1], -1, 0
	v_writelane_b32 v244, s0, 5
	s_cmpk_lt_i32 s24, 0x400
	v_mov_b32_e32 v191, 0xc61c4000
	v_writelane_b32 v244, s1, 6
	s_cselect_b64 s[0:1], -1, 0
	v_writelane_b32 v244, s0, 7
	v_mov_b32_e32 v192, 0x3400
	v_mov_b32_e32 v193, 0x4800
	v_writelane_b32 v244, s1, 8
	s_lshl_b32 s0, s24, 4
	s_and_b32 s0, s0, 0x70
	s_bfe_u32 s1, s24, 0x40003
	s_or_b32 s0, s0, s1
	s_lshl_b32 s0, s0, 7
	v_writelane_b32 v244, s0, 9
	s_and_b32 s0, s24, 0xffffff80
	v_writelane_b32 v244, s0, 10
	s_add_u32 s0, s10, 0xec81040
	s_addc_u32 s1, s11, 0
	v_writelane_b32 v244, s0, 11
	v_mov_b32_e32 v212, v143
	v_mov_b32_e32 v213, v143
	v_writelane_b32 v244, s1, 12
	s_add_u32 s0, s10, 0xa100000
	s_addc_u32 s1, s11, 0
	v_writelane_b32 v244, s0, 13
	v_mov_b32_e32 v214, v143
	v_mov_b32_e32 v215, v143
	v_writelane_b32 v244, s1, 14
	s_add_u32 s0, s10, 0xd100000
	s_addc_u32 s1, s11, 0
	v_writelane_b32 v244, s0, 15
	v_mov_b32_e32 v194, 0x4100
	v_mov_b32_e32 v195, 0x42800000
	v_writelane_b32 v244, s1, 16
	s_add_u32 s0, s10, 0xec00000
	s_addc_u32 s1, s11, 0
	v_writelane_b32 v244, s0, 17
	v_mov_b32_e32 v196, 0x42000000
	v_mov_b32_e32 v197, 0x37000000
	v_writelane_b32 v244, s1, 18
	s_add_u32 s0, s10, 0x1224000
	s_addc_u32 s1, s11, 0
	v_writelane_b32 v244, s0, 19
	v_mov_b32_e32 v198, 1
	s_nop 0
	v_writelane_b32 v244, s1, 20
	s_add_u32 s0, s10, 0xec40000
	s_addc_u32 s1, s11, 0
	v_writelane_b32 v244, s0, 21
	s_nop 1
	v_writelane_b32 v244, s1, 22
	s_add_u32 s0, s10, 0xe100000
	s_addc_u32 s1, s11, 0
	v_writelane_b32 v244, s0, 23
	s_nop 1
	v_writelane_b32 v244, s1, 24
	s_add_u32 s0, s10, 0xec81000
	s_addc_u32 s1, s11, 0
	v_writelane_b32 v244, s0, 25
	s_nop 1
	v_writelane_b32 v244, s1, 26
	s_add_u32 s0, s10, 0x1020000
	v_writelane_b32 v244, s0, 27
	s_addc_u32 s0, s11, 0
	v_writelane_b32 v244, s0, 28
	s_add_u32 s0, s10, 0xb100000
	s_addc_u32 s1, s11, 0
	v_writelane_b32 v244, s0, 29
	s_nop 1
	v_writelane_b32 v244, s1, 30
	s_add_u32 s0, s10, 0xc100000
	s_addc_u32 s1, s11, 0
	v_writelane_b32 v244, s0, 31
	s_nop 1
	v_writelane_b32 v244, s1, 32
; DI int tid_() { int t = __builtin_amdgcn_workitem_id_x(); asm volatile("" : "+v"(t)); return t; }
; DI unsigned xb_ld(unsigned* p) { return __hip_atomic_load(p, __ATOMIC_RELAXED, __HIP_MEMORY_SCOPE_AGENT); }
; DI unsigned xb_add(unsigned* p, unsigned v) { return __hip_atomic_fetch_add(p, v, __ATOMIC_RELAXED, __HIP_MEMORY_SCOPE_AGENT); }
; DI unsigned xb_xcc_id() { return (unsigned)__builtin_amdgcn_s_getreg((3 << 11) | 20) & 0xFu; }
; __global__ void __launch_bounds__(256, 2) mega(Params p, int ph0, int ph1, int coop) {
;     ...
;   XB xb; xb.x = xb_xcc_id(); xb.nloc = 1u; xb.nx = 1u;
;   unsigned* bar = (unsigned*)(p.ws + OFF_BAR);
;   if (coop && tid_() == 0) xb_add(bar + XB_XCNT(xb.x), 1u);
;   for (int ph = ph0; ph < ph1; ++ph) {
;     const Params& q = p;
;     run_phase(q, ph, smem);
;     ...
;     { const int sp = (ph - 1) % 12; const int l = (ph - 1) / 12;
;       if (ph > 0 && PROBE_DUP == 1 && (sp == 0 || sp == 9)) { cg::this_grid().sync(); run_phase(q, ph, smem); }
;       if (ph > 0 && PROBE_DUP == 2 && sp == 5) { cg::this_grid().sync(); m1_phase(q, l, smem, 32, 32); }
;       if (ph > 0 && PROBE_DUP == 3 && sp == 6) { cg::this_grid().sync(); m2_phase(q, l, smem, 48); }
;       if (ph > 0 && PROBE_DUP == 6 && sp == 6) { cg::this_grid().sync(); for (int it = blockIdx.x; it < 1024; it += gridDim.x) gdn_g3(q, l, it, smem); }
;       if (ph > 0 && PROBE_DUP == 7 && sp == 4) { cg::this_grid().sync(); for (int it = blockIdx.x; it < 2560; it += gridDim.x) vt_tile(q, it, smem); }
;       if (PROBE_DUP == 8 && ph < 20) { cg::this_grid().sync(); cg::this_grid().sync(); }
;       if (ph > 0 && PROBE_DUP == 4 && sp == 3) { cg::this_grid().sync(); run_phase(q, ph, smem); }
;       if (ph > 0 && PROBE_DUP == 5 && sp == 4) { cg::this_grid().sync(); for (int it = blockIdx.x; it < 2560 + 1024; it += gridDim.x) { if (it < 1024) gdn_g1(q, l, it, smem); else vt_tile(q, it - 1024, smem); } } }
;     ...
;     if (coop && ph + 1 < ph1) {
;       if (ph == 0) { cg::this_grid().sync();
;         unsigned mine = 0u, cnt = 0u;
;         for (unsigned j = 0; j < 16; ++j) { const unsigned c = xb_ld(bar + XB_XCNT(j)); cnt += c > 0u ? 1u : 0u; mine = (j == xb.x) ? c : mine; }
;         xb.nloc = mine > 0u ? mine : 1u; xb.nx = cnt > 0u ? cnt : 1u; }
	s_add_u32 s0, s10, 0xec80000
	v_writelane_b32 v244, s0, 33
	s_addc_u32 s0, s11, 0
	s_cmp_eq_u32 s24, 0
	v_writelane_b32 v244, s0, 34
	s_cselect_b64 s[0:1], -1, 0
	v_writelane_b32 v244, s0, 35
	s_cmpk_lt_i32 s24, 0xe00
	s_nop 0
	v_writelane_b32 v244, s1, 36
	s_cselect_b64 s[0:1], -1, 0
	v_writelane_b32 v244, s0, 37
	s_cmpk_lt_i32 s24, 0xd00
	s_nop 0
	v_writelane_b32 v244, s1, 38
	s_cselect_b64 s[0:1], -1, 0
	v_writelane_b32 v244, s0, 39
	s_nop 1
	v_writelane_b32 v244, s1, 40
	s_add_u32 s0, s10, 0xea00000
	s_addc_u32 s1, s11, 0
	v_writelane_b32 v244, s0, 41
	s_nop 1
	v_writelane_b32 v244, s1, 42
	s_add_u32 s0, s10, 0xeb00000
	s_addc_u32 s1, s11, 0
	v_writelane_b32 v244, s0, 43
	s_nop 1
	v_writelane_b32 v244, s1, 44
	s_add_u32 s0, s10, 0xe980000
	s_addc_u32 s1, s11, 0
	v_writelane_b32 v244, s0, 45
	s_cmpk_lt_i32 s24, 0x1600
	s_nop 0
	v_writelane_b32 v244, s1, 46
	s_cselect_b64 s[0:1], -1, 0
	v_writelane_b32 v244, s0, 47
	s_nop 1
	v_writelane_b32 v244, s1, 48
	s_lshl_b64 s[0:1], s[24:25], 8
	v_writelane_b32 v244, s0, 49
	s_nop 1
	v_writelane_b32 v244, s1, 50
	s_lshl_b32 s0, s6, 8
	s_add_u32 s0, s4, s0
	s_addc_u32 s1, s5, 0
	s_add_u32 s4, s0, 0x1000
	s_addc_u32 s5, s1, 0
	v_writelane_b32 v244, s4, 51
	s_add_u32 s0, s0, 0x2000
	s_addc_u32 s1, s1, 0
	v_writelane_b32 v244, s5, 52
	v_writelane_b32 v244, s0, 53
	s_nop 1
	v_writelane_b32 v244, s1, 54
	s_add_u32 s0, s10, 0xec84200
	s_addc_u32 s1, s11, 0
	v_writelane_b32 v244, s0, 55
	s_nop 1
	v_writelane_b32 v244, s1, 56
	s_add_u32 s0, s10, 0xec84300
	s_addc_u32 s1, s11, 0
	v_writelane_b32 v244, s0, 57
	s_cmp_eq_u32 s6, 0
	s_nop 0
	v_writelane_b32 v244, s1, 58
	v_cmp_eq_u32_e64 s[0:1], 0, v0
	s_nop 1
	v_writelane_b32 v244, s0, 59
	s_nop 1
	v_writelane_b32 v244, s1, 60
	s_cselect_b64 s[0:1], -1, 0
	v_writelane_b32 v244, s0, 61
	s_nop 1
	v_writelane_b32 v244, s1, 62
	s_add_u32 s0, s10, 0xec81300
	s_addc_u32 s1, s11, 0
	v_writelane_b32 v244, s0, 63
	s_cmp_eq_u32 s6, 1
	s_nop 0
	v_writelane_b32 v243, s1, 0
	s_cselect_b64 s[0:1], -1, 0
	v_writelane_b32 v243, s0, 1
	s_nop 1
	v_writelane_b32 v243, s1, 2
	s_add_u32 s0, s10, 0xec81400
	s_addc_u32 s1, s11, 0
	v_writelane_b32 v243, s0, 3
	s_cmp_eq_u32 s6, 2
	s_nop 0
	v_writelane_b32 v243, s1, 4
	s_cselect_b64 s[0:1], -1, 0
	v_writelane_b32 v243, s0, 5
	s_nop 1
	v_writelane_b32 v243, s1, 6
	s_add_u32 s0, s10, 0xec81500
	s_addc_u32 s1, s11, 0
	v_writelane_b32 v243, s0, 7
	s_cmp_eq_u32 s6, 3
	s_nop 0
	v_writelane_b32 v243, s1, 8
	s_cselect_b64 s[0:1], -1, 0
	v_writelane_b32 v243, s0, 9
	s_nop 1
	v_writelane_b32 v243, s1, 10
	s_add_u32 s0, s10, 0xec81600
	s_addc_u32 s1, s11, 0
	v_writelane_b32 v243, s0, 11
	s_cmp_eq_u32 s6, 4
	s_nop 0
	v_writelane_b32 v243, s1, 12
	s_cselect_b64 s[0:1], -1, 0
	v_writelane_b32 v243, s0, 13
	s_nop 1
	v_writelane_b32 v243, s1, 14
	s_add_u32 s0, s10, 0xec81700
	s_addc_u32 s1, s11, 0
	v_writelane_b32 v243, s0, 15
	s_cmp_eq_u32 s6, 5
	s_nop 0
	v_writelane_b32 v243, s1, 16
	s_cselect_b64 s[0:1], -1, 0
	v_writelane_b32 v243, s0, 17
	s_nop 1
	v_writelane_b32 v243, s1, 18
	s_add_u32 s0, s10, 0xec81800
	s_addc_u32 s1, s11, 0
	v_writelane_b32 v243, s0, 19
	s_cmp_eq_u32 s6, 6
	s_nop 0
	v_writelane_b32 v243, s1, 20
	s_cselect_b64 s[0:1], -1, 0
	v_writelane_b32 v243, s0, 21
	s_nop 1
	v_writelane_b32 v243, s1, 22
	s_add_u32 s0, s10, 0xec81900
	s_addc_u32 s1, s11, 0
	v_writelane_b32 v243, s0, 23
	s_cmp_eq_u32 s6, 7
	s_nop 0
	v_writelane_b32 v243, s1, 24
	s_cselect_b64 s[0:1], -1, 0
	v_writelane_b32 v243, s0, 25
	s_nop 1
	v_writelane_b32 v243, s1, 26
	s_add_u32 s0, s10, 0xec81a00
	s_addc_u32 s1, s11, 0
	v_writelane_b32 v243, s0, 27
	s_cmp_eq_u32 s6, 8
	s_nop 0
	v_writelane_b32 v243, s1, 28
	s_cselect_b64 s[0:1], -1, 0
	v_writelane_b32 v243, s0, 29
	s_nop 1
	v_writelane_b32 v243, s1, 30
	s_add_u32 s0, s10, 0xec81b00
	s_addc_u32 s1, s11, 0
	v_writelane_b32 v243, s0, 31
	s_cmp_eq_u32 s6, 9
	s_nop 0
	v_writelane_b32 v243, s1, 32
	s_cselect_b64 s[0:1], -1, 0
	v_writelane_b32 v243, s0, 33
	s_nop 1
	v_writelane_b32 v243, s1, 34
	s_add_u32 s0, s10, 0xec81c00
	s_addc_u32 s1, s11, 0
	v_writelane_b32 v243, s0, 35
	s_cmp_eq_u32 s6, 10
	s_nop 0
	v_writelane_b32 v243, s1, 36
	s_cselect_b64 s[0:1], -1, 0
	v_writelane_b32 v243, s0, 37
	s_nop 1
	v_writelane_b32 v243, s1, 38
	s_add_u32 s0, s10, 0xec81d00
	s_addc_u32 s1, s11, 0
	v_writelane_b32 v243, s0, 39
	s_cmp_eq_u32 s6, 11
	s_nop 0
	v_writelane_b32 v243, s1, 40
	s_cselect_b64 s[0:1], -1, 0
	v_writelane_b32 v243, s0, 41
	s_nop 1
	v_writelane_b32 v243, s1, 42
	s_add_u32 s0, s10, 0xec81e00
	s_addc_u32 s1, s11, 0
	v_writelane_b32 v243, s0, 43
	s_cmp_eq_u32 s6, 12
	s_nop 0
	v_writelane_b32 v243, s1, 44
	s_cselect_b64 s[0:1], -1, 0
	v_writelane_b32 v243, s0, 45
	s_nop 1
	v_writelane_b32 v243, s1, 46
	s_add_u32 s0, s10, 0xec81f00
	s_addc_u32 s1, s11, 0
	v_writelane_b32 v243, s0, 47
	s_cmp_eq_u32 s6, 13
	s_nop 0
	v_writelane_b32 v243, s1, 48
	s_cselect_b64 s[0:1], -1, 0
	v_writelane_b32 v243, s0, 49
	s_nop 1
	v_writelane_b32 v243, s1, 50
	s_add_u32 s0, s10, 0xec82000
	s_addc_u32 s1, s11, 0
	v_writelane_b32 v243, s0, 51
	s_cmp_eq_u32 s6, 14
	s_nop 0
	v_writelane_b32 v243, s1, 52
	s_cselect_b64 s[0:1], -1, 0
	v_writelane_b32 v243, s0, 53
	s_nop 1
	v_writelane_b32 v243, s1, 54
	s_add_u32 s0, s10, 0xec82100
	s_addc_u32 s1, s11, 0
	v_writelane_b32 v243, s0, 55
	s_cmp_eq_u32 s6, 15
	s_nop 0
	v_writelane_b32 v243, s1, 56
	s_cselect_b64 s[0:1], -1, 0
	v_writelane_b32 v243, s0, 57
	s_nop 1
	v_writelane_b32 v243, s1, 58
	s_lshl_b64 s[0:1], s[24:25], 12
	s_add_u32 s0, s36, s0
	v_writelane_b32 v243, s36, 59
	s_addc_u32 s1, s37, s1
	s_nop 0
	v_writelane_b32 v242, s41, 0
	v_writelane_b32 v242, s42, 1
	v_writelane_b32 v242, s43, 2
	v_writelane_b32 v242, s44, 3
	v_writelane_b32 v242, s45, 4
	v_writelane_b32 v242, s46, 5
	v_writelane_b32 v242, s47, 6
	v_writelane_b32 v242, s48, 7
	v_writelane_b32 v242, s49, 8
	v_writelane_b32 v242, s50, 9
	v_writelane_b32 v242, s51, 10
	v_writelane_b32 v242, s0, 11
	v_writelane_b32 v243, s37, 60
	v_writelane_b32 v243, s38, 61
	v_writelane_b32 v242, s1, 12
	s_lshl_b64 s[0:1], s[24:25], 11
	s_add_u32 s0, s10, s0
	s_addc_u32 s1, s11, s1
	s_add_u32 s0, s0, 0x1900000
	s_addc_u32 s1, s1, 0
	v_writelane_b32 v242, s0, 13
	v_writelane_b32 v243, s39, 62
	s_mov_b32 s10, 0x7060302
	v_writelane_b32 v242, s1, 14
	s_mov_b32 s0, s24
	v_writelane_b32 v242, s0, 15
	v_writelane_b32 v243, s40, 63
	s_nop 0
	v_writelane_b32 v242, s1, 16
	s_lshl_b32 s0, s24, 6
	v_writelane_b32 v242, s0, 17
	s_branch .LBB0_10

; DI int tid_() { int t = __builtin_amdgcn_workitem_id_x(); asm volatile("" : "+v"(t)); return t; }
;   unsigned* ctr = (unsigned*)(p.ws + OFF_CNT) + cslot;
;   const int total = 2048, wave = tid_() >> 6;
;   bool first = true;
;   for (;;) {
;     const int it = first ? (int)blockIdx.x : q_pop(ctr, smem) + (int)gridDim.x; first = false;
;     if (it >= total) break;
;     if (it < 1024) nsa_group(p, (1023 - it) * 16 + wave * 4, (float*)smem + wave * 1152);
.Lm2_enter:
	v_readlane_b32 s0, v242, 62
	s_cmp_eq_u32 s0, 1
	s_cbranch_scc1 .Lm2_go
	s_mov_b32 s0, 1
	s_nop 3
	v_writelane_b32 v242, s0, 62
	s_branch .Lm1_entry
.Lm2_go:
	s_mov_b32 s0, 0
	s_nop 3
	v_writelane_b32 v242, s0, 62
	v_readlane_b32 s0, v242, 20
	s_mov_b32 s12, s0
	s_lshl_b32 s62, s0, 2
	v_readlane_b32 s36, v245, 36
	v_readlane_b32 s1, v242, 21
	s_mulk_i32 s0, 0x3000
	s_or_b32 s2, s62, 1
	s_or_b32 s5, s62, 2
	s_or_b32 s7, s62, 3
	s_lshl_b32 s63, s12, 6
	v_readlane_b32 s40, v245, 40
	v_readlane_b32 s50, v245, 50
	s_mul_hi_i32 s1, s62, 0xc00
	v_readlane_b32 s41, v245, 41
	v_readlane_b32 s51, v245, 51
	s_add_u32 s50, s40, s0
	s_mul_hi_i32 s4, s2, 0xc00
	s_mulk_i32 s2, 0xc00
	s_addc_u32 s51, s41, s1
	s_add_u32 s52, s40, s2
	v_mov_b32_e32 v0, v170
	s_mul_hi_i32 s6, s5, 0xc00
	s_mulk_i32 s5, 0xc00
	s_addc_u32 s53, s41, s4
	s_add_u32 s54, s40, s5
	v_ashrrev_i32_e32 v0, 6, v0
	s_mul_hi_i32 s8, s7, 0xc00
	s_mulk_i32 s7, 0xc00
	s_movk_i32 s9, 0x1200
	s_addc_u32 s55, s41, s6
	v_mul_lo_u32 v120, v0, s9
	s_add_u32 s56, s40, s7
	v_readlane_b32 s0, v242, 15
	v_lshlrev_b32_e32 v107, 2, v0
	s_addc_u32 s57, s41, s8
	v_add_u32_e32 v121, 0x1080, v120
	s_mov_b32 s8, s0
	v_readlane_b32 s37, v245, 37
	v_readlane_b32 s38, v245, 38
	v_readlane_b32 s39, v245, 39
	v_readlane_b32 s42, v245, 42
	v_readlane_b32 s43, v245, 43
	v_readlane_b32 s44, v245, 44
	v_readlane_b32 s45, v245, 45
	v_readlane_b32 s46, v245, 46
	v_readlane_b32 s47, v245, 47
	v_readlane_b32 s48, v245, 48
	v_readlane_b32 s49, v245, 49
	v_readlane_b32 s1, v242, 16
	s_branch .LBB0_103

; DI int tid_() { int t = __builtin_amdgcn_workitem_id_x(); asm volatile("" : "+v"(t)); return t; }
; DI void diff_item(const Params& p, int l, int b, int hh, int qb, char* smem) {
;   const bf16_t* proj = (const bf16_t*)(p.ws + OFF_BIG) + (size_t)(b * S_) * LDP;
;   const bf16_t* vt = (const bf16_t*)(p.ws + OFF_VT) + (size_t)(hh * 64) * VLD + b * S_;
;   const int q0 = qb * 128, tid = tid_(), lane = tid & 63, wave = tid >> 6, r = lane & 31, h = lane >> 5, qw0 = q0 + wave * 32, qpos = qw0 + r;
;   bf16_t* sK1 = (bf16_t*)smem; bf16_t* sK2 = sK1 + 64 * 40; bf16_t* sV = sK2 + 64 * 40;
;   float d1 = 0.f, d2 = 0.f;
;   for (int i = 0; i < 32; ++i) { d1 += p.lq1[l * 32 + i] * p.lk1[l * 32 + i]; d2 += p.lq2[l * 32 + i] * p.lk2[l * 32 + i]; }
;   asm volatile("" : "+v"(d1), "+v"(d2));
;   const float lam_init = 0.8f - 0.6f * expf(-0.3f * (float)l), lam = expf(d1) - expf(d2) + lam_init;
;   const float sl2 = 0.17677669529663687f * 1.4426950408889634f;
;   unsigned* ctr = (unsigned*)(p.ws + OFF_CNT) + cslot;
;   const int total = 32 + 64 * 24 + 256;
;   bool first = true;
;   for (;;) {
;     const int it = (first ? (int)blockIdx.x : q_pop(ctr, smem) + (int)gridDim.x) + skip; first = false;
.Lm1_entry:
	v_readlane_b32 s0, v242, 20
	s_mov_b32 s4, s0
	v_cvt_f32_i32_e32 v0, s4
	s_mov_b32 s0, 0x3fb8aa3b
	s_mov_b32 s2, 0xc2ce8ed0
	s_ashr_i32 s5, s4, 31
	v_mul_f32_e32 v0, 0xbe99999a, v0
	v_mul_f32_e32 v1, 0x3fb8aa3b, v0
	v_fma_f32 v2, v0, s0, -v1
	v_rndne_f32_e32 v3, v1
	v_fmac_f32_e32 v2, 0x32a5705f, v0
	v_sub_f32_e32 v1, v1, v3
	v_add_f32_e32 v1, v1, v2
	v_cvt_i32_f32_e32 v3, v3
	v_exp_f32_e32 v1, v1
	v_cmp_ngt_f32_e32 vcc, s2, v0
	s_mov_b32 s2, 0x42b17218
	v_readlane_b32 s1, v242, 21
	v_ldexp_f32 v1, v1, v3
	v_cndmask_b32_e32 v1, 0, v1, vcc
	v_cmp_nlt_f32_e32 vcc, s2, v0
	s_lshl_b32 s2, s4, 6
	v_writelane_b32 v242, s2, 25
	s_lshl_b64 s[6:7], s[4:5], 21
	v_writelane_b32 v242, s6, 26
	s_mov_b32 s2, s4
	s_lshl_b32 s0, s4, 5
	v_writelane_b32 v242, s7, 27
	s_lshl_b64 s[6:7], s[4:5], 13
	v_writelane_b32 v242, s6, 28
	s_ashr_i32 s1, s0, 31
	s_lshl_b64 s[4:5], s[4:5], 16
	v_writelane_b32 v242, s7, 29
	v_writelane_b32 v242, s2, 20
	v_readlane_b32 s36, v245, 20
	s_lshl_b64 s[0:1], s[0:1], 2
	v_writelane_b32 v242, s3, 21
	v_writelane_b32 v242, s4, 30
	v_readlane_b32 s46, v245, 30
	v_readlane_b32 s47, v245, 31
	v_writelane_b32 v242, s5, 31
	s_add_u32 s4, s46, s0
	s_addc_u32 s5, s47, s1
	v_readlane_b32 s48, v245, 32
	v_writelane_b32 v242, s4, 32
	v_readlane_b32 s49, v245, 33
	v_readlane_b32 s50, v245, 34
	v_writelane_b32 v242, s5, 33
	s_add_u32 s4, s48, s0
	s_addc_u32 s5, s49, s1
	v_writelane_b32 v242, s4, 34
	v_readlane_b32 s37, v245, 21
	v_readlane_b32 s38, v245, 22
	v_readlane_b32 s39, v245, 23
	v_readlane_b32 s40, v245, 24
	v_readlane_b32 s41, v245, 25
	v_readlane_b32 s42, v245, 26
	v_readlane_b32 s43, v245, 27
	v_readlane_b32 s44, v245, 28
	v_readlane_b32 s45, v245, 29
	v_readlane_b32 s51, v245, 35
	v_writelane_b32 v242, s5, 35
	s_add_u32 s4, s50, s0
	s_addc_u32 s5, s51, s1
	v_readlane_b32 s36, v245, 36
	v_writelane_b32 v242, s4, 36
	v_readlane_b32 s37, v245, 37
	s_add_u32 s0, s36, s0
	v_writelane_b32 v242, s5, 37
	s_addc_u32 s1, s37, s1
	v_writelane_b32 v242, s0, 38
	v_cndmask_b32_e32 v0, v187, v1, vcc
	v_fmamk_f32 v199, v0, 0xbf19999a, v174
	v_writelane_b32 v242, s1, 39
	v_sub_f32_e32 v200, 1.0, v199
	v_readlane_b32 s0, v242, 15
	s_mov_b32 s11, s0
	v_readlane_b32 s38, v245, 38
	v_readlane_b32 s39, v245, 39
	v_readlane_b32 s40, v245, 40
	v_readlane_b32 s41, v245, 41
	v_readlane_b32 s42, v245, 42
	v_readlane_b32 s43, v245, 43
	v_readlane_b32 s44, v245, 44
	v_readlane_b32 s45, v245, 45
	v_readlane_b32 s46, v245, 46
	v_readlane_b32 s47, v245, 47
	v_readlane_b32 s48, v245, 48
	v_readlane_b32 s49, v245, 49
	v_readlane_b32 s50, v245, 50
	v_readlane_b32 s51, v245, 51
	v_readlane_b32 s1, v242, 16
	s_branch .LBB0_501

;     ...
;     const int it = (first ? (int)blockIdx.x : q_pop(ctr, smem) + (int)gridDim.x) + skip; first = false;
;     if (it >= total) break;
;     ...
;     if (it < 32) { if (M1SEL & 1) gdn_chain(p, it, smem); }
;     else if (it < 32 + 256) { if (M1SEL & 16) nsa_compress(p, l, it - 32, smem); }
;     else { const int j = it - 288, kind = j >> 9, jj = j & 511, qb = 63 - (jj >> 3), bh = jj & 7, b = bh >> 2, hh = bh & 3;
;       if (kind == 0) { if (M1SEL & 4) diff_item(p, l, b, hh, qb, smem); } else if (kind == 1) { if (M1SEL & 8) win_item(p, b, hh, qb, smem); } else { if (M1SEL & 2) sb_item(p, b, hh, qb, smem); } }
.LBB0_501:
	v_readlane_b32 s0, v242, 62
	s_cmp_eq_u32 s0, 1
	s_cbranch_scc1 .Lm1_mode1
	s_cmpk_lt_u32 s11, 0x120
	s_cbranch_scc1 .Lm1_hdr
	s_addk_i32 s11, 0x200
	s_branch .Lm1_hdr
.Lm1_mode1:
	s_sub_i32 s11, 0x31f, s11
	s_cmpk_gt_i32 s11, 0x11f
	s_cbranch_scc1 .Lm1_hdr
	s_movk_i32 s11, 0x7ff

; DI float bf2f(bf16_t v) { return __uint_as_float(((unsigned)v) << 16); }
; DI f32x4 gldfv(const void* p) { f32x4 r; asm volatile("global_load_dwordx4 %0, %1, off" : "=v"(r) : "v"(p) : "memory"); return r; }
; DI void nsa_compress(const Params& p, int l, int item, char* smem) {
;     ...
;   const float* w1 = (kv ? p.cvw1 : p.ckw1) + (size_t)l * 2048 * 256 + lane * 4; const float* pe = (kv ? p.pev : p.pek) + (size_t)l * 2048;
;   float acc[8][4], bias[4] = {0.f, 0.f, 0.f, 0.f};
; #pragma unroll
;   for (int r = 0; r < 8; ++r) { acc[r][0] = 0.f; acc[r][1] = 0.f; acc[r][2] = 0.f; acc[r][3] = 0.f; }
;   const int i0 = wv * 512;
;   for (int ib = 0; ib < 512; ib += 8) {
;     f32x4 wr[8];
; #pragma unroll
;     for (int u = 0; u < 8; ++u) wr[u] = gldfv(w1 + (size_t)(i0 + ib + u) * 256);
;     asm volatile("s_waitcnt vmcnt(0)" : "+v"(wr[0]), "+v"(wr[1]), "+v"(wr[2]), "+v"(wr[3]), "+v"(wr[4]), "+v"(wr[5]), "+v"(wr[6]), "+v"(wr[7]) :: "memory");
; #pragma unroll
;     for (int u = 0; u < 8; ++u) { const int i = i0 + ib + u, tk = i >> 6, d = i & 63; const float pv = pe[i]; const f32x4 w = wr[u];
;       bias[0] += pv * w[0]; bias[1] += pv * w[1]; bias[2] += pv * w[2]; bias[3] += pv * w[3];
; #pragma unroll
;       for (int r = 0; r < 8; ++r) { const float xv = bf2f(X[(16 * r + tk) * 64 + d]); acc[r][0] += xv * w[0]; acc[r][1] += xv * w[1]; acc[r][2] += xv * w[2]; acc[r][3] += xv * w[3]; } }
;   }
.LBB0_547:
	s_or_b64 exec, exec, s[0:1]
	s_cmp_eq_u32 s12, 0
	s_cselect_b64 s[4:5], -1, 0
	s_cmp_lg_u32 s12, 0
	v_readlane_b32 s36, v245, 12
	s_cselect_b64 s[0:1], -1, 0
	s_and_b64 s[6:7], s[4:5], exec
	v_readlane_b32 s37, v245, 13
	v_readlane_b32 s38, v245, 14
	v_readlane_b32 s39, v245, 15
	v_readlane_b32 s40, v245, 16
	v_readlane_b32 s41, v245, 17
	v_readlane_b32 s42, v245, 18
	v_readlane_b32 s43, v245, 19
	s_cselect_b32 s2, s37, s41
	s_cselect_b32 s6, s36, s40
	v_readlane_b32 s36, v245, 36
	s_waitcnt vmcnt(8)
	v_ashrrev_i32_e32 v78, 6, v33
	v_readlane_b32 s48, v245, 48
	v_readlane_b32 s49, v245, 49
	v_readlane_b32 s50, v245, 50
	v_readlane_b32 s51, v245, 51
	v_readlane_b32 s14, v242, 26
	v_and_b32_e32 v77, 63, v33
	s_cselect_b32 s12, s49, s51
	s_cselect_b32 s13, s48, s50
	v_readlane_b32 s15, v242, 27
	s_add_u32 s6, s6, s14
	v_lshlrev_b32_e32 v34, 9, v78
	s_addc_u32 s7, s2, s15
	v_lshlrev_b32_e32 v142, 4, v77
	v_ashrrev_i32_e32 v35, 31, v34
	v_lshl_add_u64 v[0:1], s[6:7], 0, v[142:143]
	v_lshlrev_b64 v[2:3], 10, v[34:35]
	v_lshl_add_u64 v[0:1], v[0:1], 0, v[2:3]
	s_mov_b64 s[6:7], 0x1c00
	v_lshl_add_u64 v[36:37], v[0:1], 0, s[6:7]
	v_readlane_b32 s6, v242, 28
	v_readlane_b32 s7, v242, 29
	s_add_u32 s6, s13, s6
	s_addc_u32 s7, s12, s7
	v_lshl_add_u64 v[0:1], v[34:35], 2, s[6:7]
	v_mov_b32_e32 v74, 0
	v_lshlrev_b32_e32 v32, 2, v77
	v_lshl_add_u64 v[50:51], v[0:1], 0, 28
	s_mov_b32 s6, -8
	v_mov_b32_e32 v75, v74
	v_mov_b32_e32 v68, v74
	v_mov_b32_e32 v69, v74
	v_mov_b32_e32 v72, v74
	v_mov_b32_e32 v73, v74
	v_mov_b32_e32 v70, v74
	v_mov_b32_e32 v71, v74
	v_mov_b32_e32 v64, v74
	v_mov_b32_e32 v65, v74
	v_mov_b32_e32 v66, v74
	v_mov_b32_e32 v67, v74
	v_mov_b32_e32 v60, v74
	v_mov_b32_e32 v61, v74
	v_mov_b32_e32 v62, v74
	v_mov_b32_e32 v63, v74
	v_mov_b32_e32 v56, v74
	v_mov_b32_e32 v57, v74
	v_mov_b32_e32 v58, v74
	v_mov_b32_e32 v59, v74
	v_mov_b32_e32 v52, v74
	v_mov_b32_e32 v53, v74
	v_mov_b32_e32 v54, v74
	v_mov_b32_e32 v55, v74
	v_mov_b32_e32 v46, v74
	v_mov_b32_e32 v47, v74
	v_mov_b32_e32 v48, v74
	v_mov_b32_e32 v49, v74
	v_mov_b32_e32 v42, v74
	v_mov_b32_e32 v43, v74
	v_mov_b32_e32 v44, v74
	v_mov_b32_e32 v45, v74
	v_mov_b32_e32 v38, v74
	v_mov_b32_e32 v39, v74
	v_mov_b32_e32 v40, v74
	v_mov_b32_e32 v41, v74
	s_mov_b64 s[12:13], 0x2000
	s_waitcnt lgkmcnt(0)
	s_barrier
	v_readlane_b32 s37, v245, 37
	v_readlane_b32 s38, v245, 38
	v_readlane_b32 s39, v245, 39
	v_readlane_b32 s40, v245, 40
	v_readlane_b32 s41, v245, 41
	v_readlane_b32 s42, v245, 42
	v_readlane_b32 s43, v245, 43
	v_readlane_b32 s44, v245, 44
	v_readlane_b32 s45, v245, 45
	v_readlane_b32 s46, v245, 46
	v_readlane_b32 s47, v245, 47
	s_movk_i32 s6, 0xe400
	s_mov_b32 s7, -1
	v_lshl_add_u64 v[202:203], v[36:37], 0, s[6:7]
	s_movk_i32 s6, 0x1000
	s_mov_b32 s7, 0
	v_lshl_add_u64 v[204:205], v[202:203], 0, s[6:7]
	v_mov_b32_e32 v206, v50
	v_mov_b32_e32 v207, v51
	v_lshlrev_b32_e32 v208, 1, v34
	v_mov_b32_e32 v112, 0
	v_mov_b32_e32 v113, 0
	v_mov_b32_e32 v114, 0
	v_mov_b32_e32 v115, 0
	v_mov_b32_e32 v116, 0
	v_mov_b32_e32 v117, 0
	v_mov_b32_e32 v118, 0
	v_mov_b32_e32 v119, 0
	v_mov_b32_e32 v120, 0
	v_mov_b32_e32 v121, 0
	v_mov_b32_e32 v122, 0
	v_mov_b32_e32 v123, 0
	v_mov_b32_e32 v124, 0
	v_mov_b32_e32 v125, 0
	v_mov_b32_e32 v126, 0
	v_mov_b32_e32 v127, 0
	v_mov_b32_e32 v128, 0
	v_mov_b32_e32 v129, 0
	v_mov_b32_e32 v130, 0
	v_mov_b32_e32 v131, 0
	v_mov_b32_e32 v132, 0
	v_mov_b32_e32 v133, 0
	v_mov_b32_e32 v134, 0
	v_mov_b32_e32 v135, 0
	v_mov_b32_e32 v136, 0
	v_mov_b32_e32 v137, 0
	v_mov_b32_e32 v138, 0
	v_mov_b32_e32 v139, 0
	v_mov_b32_e32 v72, 0
	v_mov_b32_e32 v73, 0
	v_mov_b32_e32 v74, 0
	v_mov_b32_e32 v75, 0
	v_mov_b32_e32 v146, 0
	v_mov_b32_e32 v147, 0
	v_mov_b32_e32 v148, 0
	v_mov_b32_e32 v149, 0
	global_load_dwordx4 v[0:3], v[202:203], off
	global_load_dwordx4 v[4:7], v[202:203], off offset:1024
	global_load_dwordx4 v[8:11], v[202:203], off offset:2048
	global_load_dwordx4 v[12:15], v[202:203], off offset:3072
	global_load_dwordx4 v[16:19], v[204:205], off
	global_load_dwordx4 v[20:23], v[204:205], off offset:1024
	global_load_dwordx4 v[24:27], v[204:205], off offset:2048
	global_load_dwordx4 v[28:31], v[204:205], off offset:3072
	global_load_dwordx4 v[150:153], v[206:207], off offset:-28
	global_load_dwordx4 v[154:157], v[206:207], off offset:-12
	v_lshl_add_u64 v[202:203], v[202:203], 0, s[12:13]
	v_lshl_add_u64 v[204:205], v[204:205], 0, s[12:13]
	v_lshl_add_u64 v[206:207], v[206:207], 0, 32
	s_mov_b32 s2, 0
; DI float bf2f(bf16_t v) { return __uint_as_float(((unsigned)v) << 16); }
; DI f32x4 gldfv(const void* p) { f32x4 r; asm volatile("global_load_dwordx4 %0, %1, off" : "=v"(r) : "v"(p) : "memory"); return r; }
; DI void nsa_compress(const Params& p, int l, int item, char* smem) {
;     ...
;   for (int ib = 0; ib < 512; ib += 8) {
;     f32x4 wr[8];
; #pragma unroll
;     for (int u = 0; u < 8; ++u) wr[u] = gldfv(w1 + (size_t)(i0 + ib + u) * 256);
;     asm volatile("s_waitcnt vmcnt(0)" : "+v"(wr[0]), "+v"(wr[1]), "+v"(wr[2]), "+v"(wr[3]), "+v"(wr[4]), "+v"(wr[5]), "+v"(wr[6]), "+v"(wr[7]) :: "memory");
; #pragma unroll
;     for (int u = 0; u < 8; ++u) { const int i = i0 + ib + u, tk = i >> 6, d = i & 63; const float pv = pe[i]; const f32x4 w = wr[u];
;       bias[0] += pv * w[0]; bias[1] += pv * w[1]; bias[2] += pv * w[2]; bias[3] += pv * w[3];
; #pragma unroll
;       for (int r = 0; r < 8; ++r) { const float xv = bf2f(X[(16 * r + tk) * 64 + d]); acc[r][0] += xv * w[0]; acc[r][1] += xv * w[1]; acc[r][2] += xv * w[2]; acc[r][3] += xv * w[3]; } }
.Lcmp_loop:
	global_load_dwordx4 v[40:43], v[202:203], off
	global_load_dwordx4 v[44:47], v[202:203], off offset:1024
	global_load_dwordx4 v[48:51], v[202:203], off offset:2048
	global_load_dwordx4 v[52:55], v[202:203], off offset:3072
	global_load_dwordx4 v[56:59], v[204:205], off
	global_load_dwordx4 v[60:63], v[204:205], off offset:1024
	global_load_dwordx4 v[64:67], v[204:205], off offset:2048
	global_load_dwordx4 v[68:71], v[204:205], off offset:3072
	global_load_dwordx4 v[216:219], v[206:207], off offset:-28
	global_load_dwordx4 v[220:223], v[206:207], off offset:-12
	v_lshl_add_u64 v[202:203], v[202:203], 0, s[12:13]
	v_lshl_add_u64 v[204:205], v[204:205], 0, s[12:13]
	v_lshl_add_u64 v[206:207], v[206:207], 0, 32
	ds_read_b128 v[80:83], v208
	ds_read_b128 v[84:87], v208 offset:2048
	ds_read_b128 v[88:91], v208 offset:4096
	ds_read_b128 v[92:95], v208 offset:6144
	ds_read_b128 v[96:99], v208 offset:8192
	ds_read_b128 v[100:103], v208 offset:10240
	ds_read_b128 v[104:107], v208 offset:12288
	ds_read_b128 v[108:111], v208 offset:14336
	v_add_u32_e32 v208, 16, v208
	s_waitcnt vmcnt(10)
	s_waitcnt lgkmcnt(0)
	v_pk_fma_f32 v[146:147], v[0:1], v[150:151], v[146:147] op_sel_hi:[1,0,1]
	v_pk_fma_f32 v[148:149], v[2:3], v[150:151], v[148:149] op_sel_hi:[1,0,1]
	v_lshlrev_b32_e32 v158, 16, v80
	v_pk_fma_f32 v[112:113], v[0:1], v[158:159], v[112:113] op_sel_hi:[1,0,1]
	v_pk_fma_f32 v[114:115], v[2:3], v[158:159], v[114:115] op_sel_hi:[1,0,1]
	v_lshlrev_b32_e32 v160, 16, v84
	v_pk_fma_f32 v[116:117], v[0:1], v[160:161], v[116:117] op_sel_hi:[1,0,1]
	v_pk_fma_f32 v[118:119], v[2:3], v[160:161], v[118:119] op_sel_hi:[1,0,1]
	v_lshlrev_b32_e32 v162, 16, v88
	v_pk_fma_f32 v[120:121], v[0:1], v[162:163], v[120:121] op_sel_hi:[1,0,1]
	v_pk_fma_f32 v[122:123], v[2:3], v[162:163], v[122:123] op_sel_hi:[1,0,1]
	v_lshlrev_b32_e32 v164, 16, v92
	v_pk_fma_f32 v[124:125], v[0:1], v[164:165], v[124:125] op_sel_hi:[1,0,1]
	v_pk_fma_f32 v[126:127], v[2:3], v[164:165], v[126:127] op_sel_hi:[1,0,1]
	v_lshlrev_b32_e32 v158, 16, v96
	v_pk_fma_f32 v[128:129], v[0:1], v[158:159], v[128:129] op_sel_hi:[1,0,1]
	v_pk_fma_f32 v[130:131], v[2:3], v[158:159], v[130:131] op_sel_hi:[1,0,1]
	v_lshlrev_b32_e32 v160, 16, v100
	v_pk_fma_f32 v[132:133], v[0:1], v[160:161], v[132:133] op_sel_hi:[1,0,1]
	v_pk_fma_f32 v[134:135], v[2:3], v[160:161], v[134:135] op_sel_hi:[1,0,1]
	v_lshlrev_b32_e32 v162, 16, v104
	v_pk_fma_f32 v[136:137], v[0:1], v[162:163], v[136:137] op_sel_hi:[1,0,1]
	v_pk_fma_f32 v[138:139], v[2:3], v[162:163], v[138:139] op_sel_hi:[1,0,1]
	v_lshlrev_b32_e32 v164, 16, v108
	v_pk_fma_f32 v[72:73], v[0:1], v[164:165], v[72:73] op_sel_hi:[1,0,1]
	v_pk_fma_f32 v[74:75], v[2:3], v[164:165], v[74:75] op_sel_hi:[1,0,1]
	v_mov_b32_e32 v166, v151
	v_pk_fma_f32 v[146:147], v[4:5], v[166:167], v[146:147] op_sel_hi:[1,0,1]
	v_pk_fma_f32 v[148:149], v[6:7], v[166:167], v[148:149] op_sel_hi:[1,0,1]
	v_and_b32_e32 v158, 0xffff0000, v80
	v_pk_fma_f32 v[112:113], v[4:5], v[158:159], v[112:113] op_sel_hi:[1,0,1]
	v_pk_fma_f32 v[114:115], v[6:7], v[158:159], v[114:115] op_sel_hi:[1,0,1]
	v_and_b32_e32 v160, 0xffff0000, v84
	v_pk_fma_f32 v[116:117], v[4:5], v[160:161], v[116:117] op_sel_hi:[1,0,1]
	v_pk_fma_f32 v[118:119], v[6:7], v[160:161], v[118:119] op_sel_hi:[1,0,1]
	v_and_b32_e32 v162, 0xffff0000, v88
	v_pk_fma_f32 v[120:121], v[4:5], v[162:163], v[120:121] op_sel_hi:[1,0,1]
	v_pk_fma_f32 v[122:123], v[6:7], v[162:163], v[122:123] op_sel_hi:[1,0,1]
	v_and_b32_e32 v164, 0xffff0000, v92
	v_pk_fma_f32 v[124:125], v[4:5], v[164:165], v[124:125] op_sel_hi:[1,0,1]
	v_pk_fma_f32 v[126:127], v[6:7], v[164:165], v[126:127] op_sel_hi:[1,0,1]
	v_and_b32_e32 v158, 0xffff0000, v96
	v_pk_fma_f32 v[128:129], v[4:5], v[158:159], v[128:129] op_sel_hi:[1,0,1]
	v_pk_fma_f32 v[130:131], v[6:7], v[158:159], v[130:131] op_sel_hi:[1,0,1]
	v_and_b32_e32 v160, 0xffff0000, v100
	v_pk_fma_f32 v[132:133], v[4:5], v[160:161], v[132:133] op_sel_hi:[1,0,1]
	v_pk_fma_f32 v[134:135], v[6:7], v[160:161], v[134:135] op_sel_hi:[1,0,1]
	v_and_b32_e32 v162, 0xffff0000, v104
	v_pk_fma_f32 v[136:137], v[4:5], v[162:163], v[136:137] op_sel_hi:[1,0,1]
	v_pk_fma_f32 v[138:139], v[6:7], v[162:163], v[138:139] op_sel_hi:[1,0,1]
	v_and_b32_e32 v164, 0xffff0000, v108
	v_pk_fma_f32 v[72:73], v[4:5], v[164:165], v[72:73] op_sel_hi:[1,0,1]
	v_pk_fma_f32 v[74:75], v[6:7], v[164:165], v[74:75] op_sel_hi:[1,0,1]
	v_pk_fma_f32 v[146:147], v[8:9], v[152:153], v[146:147] op_sel_hi:[1,0,1]
	v_pk_fma_f32 v[148:149], v[10:11], v[152:153], v[148:149] op_sel_hi:[1,0,1]
	v_lshlrev_b32_e32 v158, 16, v81
	v_pk_fma_f32 v[112:113], v[8:9], v[158:159], v[112:113] op_sel_hi:[1,0,1]
	v_pk_fma_f32 v[114:115], v[10:11], v[158:159], v[114:115] op_sel_hi:[1,0,1]
	v_lshlrev_b32_e32 v160, 16, v85
	v_pk_fma_f32 v[116:117], v[8:9], v[160:161], v[116:117] op_sel_hi:[1,0,1]
	v_pk_fma_f32 v[118:119], v[10:11], v[160:161], v[118:119] op_sel_hi:[1,0,1]
	v_lshlrev_b32_e32 v162, 16, v89
	v_pk_fma_f32 v[120:121], v[8:9], v[162:163], v[120:121] op_sel_hi:[1,0,1]
	v_pk_fma_f32 v[122:123], v[10:11], v[162:163], v[122:123] op_sel_hi:[1,0,1]
	v_lshlrev_b32_e32 v164, 16, v93
	v_pk_fma_f32 v[124:125], v[8:9], v[164:165], v[124:125] op_sel_hi:[1,0,1]
	v_pk_fma_f32 v[126:127], v[10:11], v[164:165], v[126:127] op_sel_hi:[1,0,1]
	v_lshlrev_b32_e32 v158, 16, v97
	v_pk_fma_f32 v[128:129], v[8:9], v[158:159], v[128:129] op_sel_hi:[1,0,1]
	v_pk_fma_f32 v[130:131], v[10:11], v[158:159], v[130:131] op_sel_hi:[1,0,1]
	v_lshlrev_b32_e32 v160, 16, v101
	v_pk_fma_f32 v[132:133], v[8:9], v[160:161], v[132:133] op_sel_hi:[1,0,1]
	v_pk_fma_f32 v[134:135], v[10:11], v[160:161], v[134:135] op_sel_hi:[1,0,1]
; DI float bf2f(bf16_t v) { return __uint_as_float(((unsigned)v) << 16); }
; DI void nsa_compress(const Params& p, int l, int item, char* smem) {
;     ...
;     for (int u = 0; u < 8; ++u) { const int i = i0 + ib + u, tk = i >> 6, d = i & 63; const float pv = pe[i]; const f32x4 w = wr[u];
;       bias[0] += pv * w[0]; bias[1] += pv * w[1]; bias[2] += pv * w[2]; bias[3] += pv * w[3];
; #pragma unroll
;       for (int r = 0; r < 8; ++r) { const float xv = bf2f(X[(16 * r + tk) * 64 + d]); acc[r][0] += xv * w[0]; acc[r][1] += xv * w[1]; acc[r][2] += xv * w[2]; acc[r][3] += xv * w[3]; } }
	v_lshlrev_b32_e32 v162, 16, v105
	v_pk_fma_f32 v[136:137], v[8:9], v[162:163], v[136:137] op_sel_hi:[1,0,1]
	v_pk_fma_f32 v[138:139], v[10:11], v[162:163], v[138:139] op_sel_hi:[1,0,1]
	v_lshlrev_b32_e32 v164, 16, v109
	v_pk_fma_f32 v[72:73], v[8:9], v[164:165], v[72:73] op_sel_hi:[1,0,1]
	v_pk_fma_f32 v[74:75], v[10:11], v[164:165], v[74:75] op_sel_hi:[1,0,1]
	v_mov_b32_e32 v166, v153
	v_pk_fma_f32 v[146:147], v[12:13], v[166:167], v[146:147] op_sel_hi:[1,0,1]
	v_pk_fma_f32 v[148:149], v[14:15], v[166:167], v[148:149] op_sel_hi:[1,0,1]
	v_and_b32_e32 v158, 0xffff0000, v81
	v_pk_fma_f32 v[112:113], v[12:13], v[158:159], v[112:113] op_sel_hi:[1,0,1]
	v_pk_fma_f32 v[114:115], v[14:15], v[158:159], v[114:115] op_sel_hi:[1,0,1]
	v_and_b32_e32 v160, 0xffff0000, v85
	v_pk_fma_f32 v[116:117], v[12:13], v[160:161], v[116:117] op_sel_hi:[1,0,1]
	v_pk_fma_f32 v[118:119], v[14:15], v[160:161], v[118:119] op_sel_hi:[1,0,1]
	v_and_b32_e32 v162, 0xffff0000, v89
	v_pk_fma_f32 v[120:121], v[12:13], v[162:163], v[120:121] op_sel_hi:[1,0,1]
	v_pk_fma_f32 v[122:123], v[14:15], v[162:163], v[122:123] op_sel_hi:[1,0,1]
	v_and_b32_e32 v164, 0xffff0000, v93
	v_pk_fma_f32 v[124:125], v[12:13], v[164:165], v[124:125] op_sel_hi:[1,0,1]
	v_pk_fma_f32 v[126:127], v[14:15], v[164:165], v[126:127] op_sel_hi:[1,0,1]
	v_and_b32_e32 v158, 0xffff0000, v97
	v_pk_fma_f32 v[128:129], v[12:13], v[158:159], v[128:129] op_sel_hi:[1,0,1]
	v_pk_fma_f32 v[130:131], v[14:15], v[158:159], v[130:131] op_sel_hi:[1,0,1]
	v_and_b32_e32 v160, 0xffff0000, v101
	v_pk_fma_f32 v[132:133], v[12:13], v[160:161], v[132:133] op_sel_hi:[1,0,1]
	v_pk_fma_f32 v[134:135], v[14:15], v[160:161], v[134:135] op_sel_hi:[1,0,1]
	v_and_b32_e32 v162, 0xffff0000, v105
	v_pk_fma_f32 v[136:137], v[12:13], v[162:163], v[136:137] op_sel_hi:[1,0,1]
	v_pk_fma_f32 v[138:139], v[14:15], v[162:163], v[138:139] op_sel_hi:[1,0,1]
	v_and_b32_e32 v164, 0xffff0000, v109
	v_pk_fma_f32 v[72:73], v[12:13], v[164:165], v[72:73] op_sel_hi:[1,0,1]
	v_pk_fma_f32 v[74:75], v[14:15], v[164:165], v[74:75] op_sel_hi:[1,0,1]
	v_pk_fma_f32 v[146:147], v[16:17], v[154:155], v[146:147] op_sel_hi:[1,0,1]
	v_pk_fma_f32 v[148:149], v[18:19], v[154:155], v[148:149] op_sel_hi:[1,0,1]
	v_lshlrev_b32_e32 v158, 16, v82
	v_pk_fma_f32 v[112:113], v[16:17], v[158:159], v[112:113] op_sel_hi:[1,0,1]
	v_pk_fma_f32 v[114:115], v[18:19], v[158:159], v[114:115] op_sel_hi:[1,0,1]
	v_lshlrev_b32_e32 v160, 16, v86
	v_pk_fma_f32 v[116:117], v[16:17], v[160:161], v[116:117] op_sel_hi:[1,0,1]
	v_pk_fma_f32 v[118:119], v[18:19], v[160:161], v[118:119] op_sel_hi:[1,0,1]
	v_lshlrev_b32_e32 v162, 16, v90
	v_pk_fma_f32 v[120:121], v[16:17], v[162:163], v[120:121] op_sel_hi:[1,0,1]
	v_pk_fma_f32 v[122:123], v[18:19], v[162:163], v[122:123] op_sel_hi:[1,0,1]
	v_lshlrev_b32_e32 v164, 16, v94
	v_pk_fma_f32 v[124:125], v[16:17], v[164:165], v[124:125] op_sel_hi:[1,0,1]
	v_pk_fma_f32 v[126:127], v[18:19], v[164:165], v[126:127] op_sel_hi:[1,0,1]
	v_lshlrev_b32_e32 v158, 16, v98
	v_pk_fma_f32 v[128:129], v[16:17], v[158:159], v[128:129] op_sel_hi:[1,0,1]
	v_pk_fma_f32 v[130:131], v[18:19], v[158:159], v[130:131] op_sel_hi:[1,0,1]
	v_lshlrev_b32_e32 v160, 16, v102
	v_pk_fma_f32 v[132:133], v[16:17], v[160:161], v[132:133] op_sel_hi:[1,0,1]
	v_pk_fma_f32 v[134:135], v[18:19], v[160:161], v[134:135] op_sel_hi:[1,0,1]
	v_lshlrev_b32_e32 v162, 16, v106
	v_pk_fma_f32 v[136:137], v[16:17], v[162:163], v[136:137] op_sel_hi:[1,0,1]
	v_pk_fma_f32 v[138:139], v[18:19], v[162:163], v[138:139] op_sel_hi:[1,0,1]
	v_lshlrev_b32_e32 v164, 16, v110
	v_pk_fma_f32 v[72:73], v[16:17], v[164:165], v[72:73] op_sel_hi:[1,0,1]
	v_pk_fma_f32 v[74:75], v[18:19], v[164:165], v[74:75] op_sel_hi:[1,0,1]
	v_mov_b32_e32 v166, v155
	v_pk_fma_f32 v[146:147], v[20:21], v[166:167], v[146:147] op_sel_hi:[1,0,1]
	v_pk_fma_f32 v[148:149], v[22:23], v[166:167], v[148:149] op_sel_hi:[1,0,1]
	v_and_b32_e32 v158, 0xffff0000, v82
	v_pk_fma_f32 v[112:113], v[20:21], v[158:159], v[112:113] op_sel_hi:[1,0,1]
	v_pk_fma_f32 v[114:115], v[22:23], v[158:159], v[114:115] op_sel_hi:[1,0,1]
	v_and_b32_e32 v160, 0xffff0000, v86
	v_pk_fma_f32 v[116:117], v[20:21], v[160:161], v[116:117] op_sel_hi:[1,0,1]
	v_pk_fma_f32 v[118:119], v[22:23], v[160:161], v[118:119] op_sel_hi:[1,0,1]
	v_and_b32_e32 v162, 0xffff0000, v90
	v_pk_fma_f32 v[120:121], v[20:21], v[162:163], v[120:121] op_sel_hi:[1,0,1]
	v_pk_fma_f32 v[122:123], v[22:23], v[162:163], v[122:123] op_sel_hi:[1,0,1]
	v_and_b32_e32 v164, 0xffff0000, v94
	v_pk_fma_f32 v[124:125], v[20:21], v[164:165], v[124:125] op_sel_hi:[1,0,1]
	v_pk_fma_f32 v[126:127], v[22:23], v[164:165], v[126:127] op_sel_hi:[1,0,1]
	v_and_b32_e32 v158, 0xffff0000, v98
	v_pk_fma_f32 v[128:129], v[20:21], v[158:159], v[128:129] op_sel_hi:[1,0,1]
	v_pk_fma_f32 v[130:131], v[22:23], v[158:159], v[130:131] op_sel_hi:[1,0,1]
	v_and_b32_e32 v160, 0xffff0000, v102
	v_pk_fma_f32 v[132:133], v[20:21], v[160:161], v[132:133] op_sel_hi:[1,0,1]
	v_pk_fma_f32 v[134:135], v[22:23], v[160:161], v[134:135] op_sel_hi:[1,0,1]
	v_and_b32_e32 v162, 0xffff0000, v106
	v_pk_fma_f32 v[136:137], v[20:21], v[162:163], v[136:137] op_sel_hi:[1,0,1]
	v_pk_fma_f32 v[138:139], v[22:23], v[162:163], v[138:139] op_sel_hi:[1,0,1]
	v_and_b32_e32 v164, 0xffff0000, v110
	v_pk_fma_f32 v[72:73], v[20:21], v[164:165], v[72:73] op_sel_hi:[1,0,1]
	v_pk_fma_f32 v[74:75], v[22:23], v[164:165], v[74:75] op_sel_hi:[1,0,1]
	v_pk_fma_f32 v[146:147], v[24:25], v[156:157], v[146:147] op_sel_hi:[1,0,1]
	v_pk_fma_f32 v[148:149], v[26:27], v[156:157], v[148:149] op_sel_hi:[1,0,1]
	v_lshlrev_b32_e32 v158, 16, v83
; DI float bf2f(bf16_t v) { return __uint_as_float(((unsigned)v) << 16); }
; DI f32x4 gldfv(const void* p) { f32x4 r; asm volatile("global_load_dwordx4 %0, %1, off" : "=v"(r) : "v"(p) : "memory"); return r; }
; DI void nsa_compress(const Params& p, int l, int item, char* smem) {
;     ...
;   for (int ib = 0; ib < 512; ib += 8) {
;     f32x4 wr[8];
; #pragma unroll
;     for (int u = 0; u < 8; ++u) wr[u] = gldfv(w1 + (size_t)(i0 + ib + u) * 256);
;     asm volatile("s_waitcnt vmcnt(0)" : "+v"(wr[0]), "+v"(wr[1]), "+v"(wr[2]), "+v"(wr[3]), "+v"(wr[4]), "+v"(wr[5]), "+v"(wr[6]), "+v"(wr[7]) :: "memory");
; #pragma unroll
;     for (int u = 0; u < 8; ++u) { const int i = i0 + ib + u, tk = i >> 6, d = i & 63; const float pv = pe[i]; const f32x4 w = wr[u];
;       bias[0] += pv * w[0]; bias[1] += pv * w[1]; bias[2] += pv * w[2]; bias[3] += pv * w[3];
; #pragma unroll
;       for (int r = 0; r < 8; ++r) { const float xv = bf2f(X[(16 * r + tk) * 64 + d]); acc[r][0] += xv * w[0]; acc[r][1] += xv * w[1]; acc[r][2] += xv * w[2]; acc[r][3] += xv * w[3]; } }
	v_pk_fma_f32 v[112:113], v[24:25], v[158:159], v[112:113] op_sel_hi:[1,0,1]
	v_pk_fma_f32 v[114:115], v[26:27], v[158:159], v[114:115] op_sel_hi:[1,0,1]
	v_lshlrev_b32_e32 v160, 16, v87
	v_pk_fma_f32 v[116:117], v[24:25], v[160:161], v[116:117] op_sel_hi:[1,0,1]
	v_pk_fma_f32 v[118:119], v[26:27], v[160:161], v[118:119] op_sel_hi:[1,0,1]
	v_lshlrev_b32_e32 v162, 16, v91
	v_pk_fma_f32 v[120:121], v[24:25], v[162:163], v[120:121] op_sel_hi:[1,0,1]
	v_pk_fma_f32 v[122:123], v[26:27], v[162:163], v[122:123] op_sel_hi:[1,0,1]
	v_lshlrev_b32_e32 v164, 16, v95
	v_pk_fma_f32 v[124:125], v[24:25], v[164:165], v[124:125] op_sel_hi:[1,0,1]
	v_pk_fma_f32 v[126:127], v[26:27], v[164:165], v[126:127] op_sel_hi:[1,0,1]
	v_lshlrev_b32_e32 v158, 16, v99
	v_pk_fma_f32 v[128:129], v[24:25], v[158:159], v[128:129] op_sel_hi:[1,0,1]
	v_pk_fma_f32 v[130:131], v[26:27], v[158:159], v[130:131] op_sel_hi:[1,0,1]
	v_lshlrev_b32_e32 v160, 16, v103
	v_pk_fma_f32 v[132:133], v[24:25], v[160:161], v[132:133] op_sel_hi:[1,0,1]
	v_pk_fma_f32 v[134:135], v[26:27], v[160:161], v[134:135] op_sel_hi:[1,0,1]
	v_lshlrev_b32_e32 v162, 16, v107
	v_pk_fma_f32 v[136:137], v[24:25], v[162:163], v[136:137] op_sel_hi:[1,0,1]
	v_pk_fma_f32 v[138:139], v[26:27], v[162:163], v[138:139] op_sel_hi:[1,0,1]
	v_lshlrev_b32_e32 v164, 16, v111
	v_pk_fma_f32 v[72:73], v[24:25], v[164:165], v[72:73] op_sel_hi:[1,0,1]
	v_pk_fma_f32 v[74:75], v[26:27], v[164:165], v[74:75] op_sel_hi:[1,0,1]
	v_mov_b32_e32 v166, v157
	v_pk_fma_f32 v[146:147], v[28:29], v[166:167], v[146:147] op_sel_hi:[1,0,1]
	v_pk_fma_f32 v[148:149], v[30:31], v[166:167], v[148:149] op_sel_hi:[1,0,1]
	v_and_b32_e32 v158, 0xffff0000, v83
	v_pk_fma_f32 v[112:113], v[28:29], v[158:159], v[112:113] op_sel_hi:[1,0,1]
	v_pk_fma_f32 v[114:115], v[30:31], v[158:159], v[114:115] op_sel_hi:[1,0,1]
	v_and_b32_e32 v160, 0xffff0000, v87
	v_pk_fma_f32 v[116:117], v[28:29], v[160:161], v[116:117] op_sel_hi:[1,0,1]
	v_pk_fma_f32 v[118:119], v[30:31], v[160:161], v[118:119] op_sel_hi:[1,0,1]
	v_and_b32_e32 v162, 0xffff0000, v91
	v_pk_fma_f32 v[120:121], v[28:29], v[162:163], v[120:121] op_sel_hi:[1,0,1]
	v_pk_fma_f32 v[122:123], v[30:31], v[162:163], v[122:123] op_sel_hi:[1,0,1]
	v_and_b32_e32 v164, 0xffff0000, v95
	v_pk_fma_f32 v[124:125], v[28:29], v[164:165], v[124:125] op_sel_hi:[1,0,1]
	v_pk_fma_f32 v[126:127], v[30:31], v[164:165], v[126:127] op_sel_hi:[1,0,1]
	v_and_b32_e32 v158, 0xffff0000, v99
	v_pk_fma_f32 v[128:129], v[28:29], v[158:159], v[128:129] op_sel_hi:[1,0,1]
	v_pk_fma_f32 v[130:131], v[30:31], v[158:159], v[130:131] op_sel_hi:[1,0,1]
	v_and_b32_e32 v160, 0xffff0000, v103
	v_pk_fma_f32 v[132:133], v[28:29], v[160:161], v[132:133] op_sel_hi:[1,0,1]
	v_pk_fma_f32 v[134:135], v[30:31], v[160:161], v[134:135] op_sel_hi:[1,0,1]
	v_and_b32_e32 v162, 0xffff0000, v107
	v_pk_fma_f32 v[136:137], v[28:29], v[162:163], v[136:137] op_sel_hi:[1,0,1]
	v_pk_fma_f32 v[138:139], v[30:31], v[162:163], v[138:139] op_sel_hi:[1,0,1]
	v_and_b32_e32 v164, 0xffff0000, v111
	v_pk_fma_f32 v[72:73], v[28:29], v[164:165], v[72:73] op_sel_hi:[1,0,1]
	v_pk_fma_f32 v[74:75], v[30:31], v[164:165], v[74:75] op_sel_hi:[1,0,1]
	global_load_dwordx4 v[0:3], v[202:203], off
	global_load_dwordx4 v[4:7], v[202:203], off offset:1024
	global_load_dwordx4 v[8:11], v[202:203], off offset:2048
	global_load_dwordx4 v[12:15], v[202:203], off offset:3072
	global_load_dwordx4 v[16:19], v[204:205], off
	global_load_dwordx4 v[20:23], v[204:205], off offset:1024
	global_load_dwordx4 v[24:27], v[204:205], off offset:2048
	global_load_dwordx4 v[28:31], v[204:205], off offset:3072
	global_load_dwordx4 v[150:153], v[206:207], off offset:-28
	global_load_dwordx4 v[154:157], v[206:207], off offset:-12
	v_lshl_add_u64 v[202:203], v[202:203], 0, s[12:13]
	v_lshl_add_u64 v[204:205], v[204:205], 0, s[12:13]
	v_lshl_add_u64 v[206:207], v[206:207], 0, 32
	ds_read_b128 v[80:83], v208
	ds_read_b128 v[84:87], v208 offset:2048
	ds_read_b128 v[88:91], v208 offset:4096
	ds_read_b128 v[92:95], v208 offset:6144
	ds_read_b128 v[96:99], v208 offset:8192
	ds_read_b128 v[100:103], v208 offset:10240
	ds_read_b128 v[104:107], v208 offset:12288
	ds_read_b128 v[108:111], v208 offset:14336
	v_add_u32_e32 v208, 16, v208
	s_waitcnt vmcnt(10)
	s_waitcnt lgkmcnt(0)
; DI float bf2f(bf16_t v) { return __uint_as_float(((unsigned)v) << 16); }
; DI void nsa_compress(const Params& p, int l, int item, char* smem) {
;     ...
;     for (int u = 0; u < 8; ++u) { const int i = i0 + ib + u, tk = i >> 6, d = i & 63; const float pv = pe[i]; const f32x4 w = wr[u];
;       bias[0] += pv * w[0]; bias[1] += pv * w[1]; bias[2] += pv * w[2]; bias[3] += pv * w[3];
; #pragma unroll
;       for (int r = 0; r < 8; ++r) { const float xv = bf2f(X[(16 * r + tk) * 64 + d]); acc[r][0] += xv * w[0]; acc[r][1] += xv * w[1]; acc[r][2] += xv * w[2]; acc[r][3] += xv * w[3]; } }
	v_pk_fma_f32 v[146:147], v[40:41], v[216:217], v[146:147] op_sel_hi:[1,0,1]
	v_pk_fma_f32 v[148:149], v[42:43], v[216:217], v[148:149] op_sel_hi:[1,0,1]
	v_lshlrev_b32_e32 v158, 16, v80
	v_pk_fma_f32 v[112:113], v[40:41], v[158:159], v[112:113] op_sel_hi:[1,0,1]
	v_pk_fma_f32 v[114:115], v[42:43], v[158:159], v[114:115] op_sel_hi:[1,0,1]
	v_lshlrev_b32_e32 v160, 16, v84
	v_pk_fma_f32 v[116:117], v[40:41], v[160:161], v[116:117] op_sel_hi:[1,0,1]
	v_pk_fma_f32 v[118:119], v[42:43], v[160:161], v[118:119] op_sel_hi:[1,0,1]
	v_lshlrev_b32_e32 v162, 16, v88
	v_pk_fma_f32 v[120:121], v[40:41], v[162:163], v[120:121] op_sel_hi:[1,0,1]
	v_pk_fma_f32 v[122:123], v[42:43], v[162:163], v[122:123] op_sel_hi:[1,0,1]
	v_lshlrev_b32_e32 v164, 16, v92
	v_pk_fma_f32 v[124:125], v[40:41], v[164:165], v[124:125] op_sel_hi:[1,0,1]
	v_pk_fma_f32 v[126:127], v[42:43], v[164:165], v[126:127] op_sel_hi:[1,0,1]
	v_lshlrev_b32_e32 v158, 16, v96
	v_pk_fma_f32 v[128:129], v[40:41], v[158:159], v[128:129] op_sel_hi:[1,0,1]
	v_pk_fma_f32 v[130:131], v[42:43], v[158:159], v[130:131] op_sel_hi:[1,0,1]
	v_lshlrev_b32_e32 v160, 16, v100
	v_pk_fma_f32 v[132:133], v[40:41], v[160:161], v[132:133] op_sel_hi:[1,0,1]
	v_pk_fma_f32 v[134:135], v[42:43], v[160:161], v[134:135] op_sel_hi:[1,0,1]
	v_lshlrev_b32_e32 v162, 16, v104
	v_pk_fma_f32 v[136:137], v[40:41], v[162:163], v[136:137] op_sel_hi:[1,0,1]
	v_pk_fma_f32 v[138:139], v[42:43], v[162:163], v[138:139] op_sel_hi:[1,0,1]
	v_lshlrev_b32_e32 v164, 16, v108
	v_pk_fma_f32 v[72:73], v[40:41], v[164:165], v[72:73] op_sel_hi:[1,0,1]
	v_pk_fma_f32 v[74:75], v[42:43], v[164:165], v[74:75] op_sel_hi:[1,0,1]
	v_mov_b32_e32 v166, v217
	v_pk_fma_f32 v[146:147], v[44:45], v[166:167], v[146:147] op_sel_hi:[1,0,1]
	v_pk_fma_f32 v[148:149], v[46:47], v[166:167], v[148:149] op_sel_hi:[1,0,1]
	v_and_b32_e32 v158, 0xffff0000, v80
	v_pk_fma_f32 v[112:113], v[44:45], v[158:159], v[112:113] op_sel_hi:[1,0,1]
	v_pk_fma_f32 v[114:115], v[46:47], v[158:159], v[114:115] op_sel_hi:[1,0,1]
	v_and_b32_e32 v160, 0xffff0000, v84
	v_pk_fma_f32 v[116:117], v[44:45], v[160:161], v[116:117] op_sel_hi:[1,0,1]
	v_pk_fma_f32 v[118:119], v[46:47], v[160:161], v[118:119] op_sel_hi:[1,0,1]
	v_and_b32_e32 v162, 0xffff0000, v88
	v_pk_fma_f32 v[120:121], v[44:45], v[162:163], v[120:121] op_sel_hi:[1,0,1]
	v_pk_fma_f32 v[122:123], v[46:47], v[162:163], v[122:123] op_sel_hi:[1,0,1]
	v_and_b32_e32 v164, 0xffff0000, v92
	v_pk_fma_f32 v[124:125], v[44:45], v[164:165], v[124:125] op_sel_hi:[1,0,1]
	v_pk_fma_f32 v[126:127], v[46:47], v[164:165], v[126:127] op_sel_hi:[1,0,1]
	v_and_b32_e32 v158, 0xffff0000, v96
	v_pk_fma_f32 v[128:129], v[44:45], v[158:159], v[128:129] op_sel_hi:[1,0,1]
	v_pk_fma_f32 v[130:131], v[46:47], v[158:159], v[130:131] op_sel_hi:[1,0,1]
	v_and_b32_e32 v160, 0xffff0000, v100
	v_pk_fma_f32 v[132:133], v[44:45], v[160:161], v[132:133] op_sel_hi:[1,0,1]
	v_pk_fma_f32 v[134:135], v[46:47], v[160:161], v[134:135] op_sel_hi:[1,0,1]
	v_and_b32_e32 v162, 0xffff0000, v104
	v_pk_fma_f32 v[136:137], v[44:45], v[162:163], v[136:137] op_sel_hi:[1,0,1]
	v_pk_fma_f32 v[138:139], v[46:47], v[162:163], v[138:139] op_sel_hi:[1,0,1]
	v_and_b32_e32 v164, 0xffff0000, v108
	v_pk_fma_f32 v[72:73], v[44:45], v[164:165], v[72:73] op_sel_hi:[1,0,1]
	v_pk_fma_f32 v[74:75], v[46:47], v[164:165], v[74:75] op_sel_hi:[1,0,1]
	v_pk_fma_f32 v[146:147], v[48:49], v[218:219], v[146:147] op_sel_hi:[1,0,1]
	v_pk_fma_f32 v[148:149], v[50:51], v[218:219], v[148:149] op_sel_hi:[1,0,1]
	v_lshlrev_b32_e32 v158, 16, v81
	v_pk_fma_f32 v[112:113], v[48:49], v[158:159], v[112:113] op_sel_hi:[1,0,1]
	v_pk_fma_f32 v[114:115], v[50:51], v[158:159], v[114:115] op_sel_hi:[1,0,1]
	v_lshlrev_b32_e32 v160, 16, v85
	v_pk_fma_f32 v[116:117], v[48:49], v[160:161], v[116:117] op_sel_hi:[1,0,1]
	v_pk_fma_f32 v[118:119], v[50:51], v[160:161], v[118:119] op_sel_hi:[1,0,1]
	v_lshlrev_b32_e32 v162, 16, v89
	v_pk_fma_f32 v[120:121], v[48:49], v[162:163], v[120:121] op_sel_hi:[1,0,1]
	v_pk_fma_f32 v[122:123], v[50:51], v[162:163], v[122:123] op_sel_hi:[1,0,1]
	v_lshlrev_b32_e32 v164, 16, v93
	v_pk_fma_f32 v[124:125], v[48:49], v[164:165], v[124:125] op_sel_hi:[1,0,1]
	v_pk_fma_f32 v[126:127], v[50:51], v[164:165], v[126:127] op_sel_hi:[1,0,1]
	v_lshlrev_b32_e32 v158, 16, v97
	v_pk_fma_f32 v[128:129], v[48:49], v[158:159], v[128:129] op_sel_hi:[1,0,1]
	v_pk_fma_f32 v[130:131], v[50:51], v[158:159], v[130:131] op_sel_hi:[1,0,1]
	v_lshlrev_b32_e32 v160, 16, v101
	v_pk_fma_f32 v[132:133], v[48:49], v[160:161], v[132:133] op_sel_hi:[1,0,1]
	v_pk_fma_f32 v[134:135], v[50:51], v[160:161], v[134:135] op_sel_hi:[1,0,1]
	v_lshlrev_b32_e32 v162, 16, v105
	v_pk_fma_f32 v[136:137], v[48:49], v[162:163], v[136:137] op_sel_hi:[1,0,1]
	v_pk_fma_f32 v[138:139], v[50:51], v[162:163], v[138:139] op_sel_hi:[1,0,1]
	v_lshlrev_b32_e32 v164, 16, v109
	v_pk_fma_f32 v[72:73], v[48:49], v[164:165], v[72:73] op_sel_hi:[1,0,1]
	v_pk_fma_f32 v[74:75], v[50:51], v[164:165], v[74:75] op_sel_hi:[1,0,1]
	v_mov_b32_e32 v166, v219
	v_pk_fma_f32 v[146:147], v[52:53], v[166:167], v[146:147] op_sel_hi:[1,0,1]
	v_pk_fma_f32 v[148:149], v[54:55], v[166:167], v[148:149] op_sel_hi:[1,0,1]
	v_and_b32_e32 v158, 0xffff0000, v81
	v_pk_fma_f32 v[112:113], v[52:53], v[158:159], v[112:113] op_sel_hi:[1,0,1]
	v_pk_fma_f32 v[114:115], v[54:55], v[158:159], v[114:115] op_sel_hi:[1,0,1]
	v_and_b32_e32 v160, 0xffff0000, v85
	v_pk_fma_f32 v[116:117], v[52:53], v[160:161], v[116:117] op_sel_hi:[1,0,1]
	v_pk_fma_f32 v[118:119], v[54:55], v[160:161], v[118:119] op_sel_hi:[1,0,1]
	v_and_b32_e32 v162, 0xffff0000, v89
	v_pk_fma_f32 v[120:121], v[52:53], v[162:163], v[120:121] op_sel_hi:[1,0,1]
; DI float bf2f(bf16_t v) { return __uint_as_float(((unsigned)v) << 16); }
; DI void nsa_compress(const Params& p, int l, int item, char* smem) {
;     ...
;     for (int u = 0; u < 8; ++u) { const int i = i0 + ib + u, tk = i >> 6, d = i & 63; const float pv = pe[i]; const f32x4 w = wr[u];
;       bias[0] += pv * w[0]; bias[1] += pv * w[1]; bias[2] += pv * w[2]; bias[3] += pv * w[3];
; #pragma unroll
;       for (int r = 0; r < 8; ++r) { const float xv = bf2f(X[(16 * r + tk) * 64 + d]); acc[r][0] += xv * w[0]; acc[r][1] += xv * w[1]; acc[r][2] += xv * w[2]; acc[r][3] += xv * w[3]; } }
	v_pk_fma_f32 v[122:123], v[54:55], v[162:163], v[122:123] op_sel_hi:[1,0,1]
	v_and_b32_e32 v164, 0xffff0000, v93
	v_pk_fma_f32 v[124:125], v[52:53], v[164:165], v[124:125] op_sel_hi:[1,0,1]
	v_pk_fma_f32 v[126:127], v[54:55], v[164:165], v[126:127] op_sel_hi:[1,0,1]
	v_and_b32_e32 v158, 0xffff0000, v97
	v_pk_fma_f32 v[128:129], v[52:53], v[158:159], v[128:129] op_sel_hi:[1,0,1]
	v_pk_fma_f32 v[130:131], v[54:55], v[158:159], v[130:131] op_sel_hi:[1,0,1]
	v_and_b32_e32 v160, 0xffff0000, v101
	v_pk_fma_f32 v[132:133], v[52:53], v[160:161], v[132:133] op_sel_hi:[1,0,1]
	v_pk_fma_f32 v[134:135], v[54:55], v[160:161], v[134:135] op_sel_hi:[1,0,1]
	v_and_b32_e32 v162, 0xffff0000, v105
	v_pk_fma_f32 v[136:137], v[52:53], v[162:163], v[136:137] op_sel_hi:[1,0,1]
	v_pk_fma_f32 v[138:139], v[54:55], v[162:163], v[138:139] op_sel_hi:[1,0,1]
	v_and_b32_e32 v164, 0xffff0000, v109
	v_pk_fma_f32 v[72:73], v[52:53], v[164:165], v[72:73] op_sel_hi:[1,0,1]
	v_pk_fma_f32 v[74:75], v[54:55], v[164:165], v[74:75] op_sel_hi:[1,0,1]
	v_pk_fma_f32 v[146:147], v[56:57], v[220:221], v[146:147] op_sel_hi:[1,0,1]
	v_pk_fma_f32 v[148:149], v[58:59], v[220:221], v[148:149] op_sel_hi:[1,0,1]
	v_lshlrev_b32_e32 v158, 16, v82
	v_pk_fma_f32 v[112:113], v[56:57], v[158:159], v[112:113] op_sel_hi:[1,0,1]
	v_pk_fma_f32 v[114:115], v[58:59], v[158:159], v[114:115] op_sel_hi:[1,0,1]
	v_lshlrev_b32_e32 v160, 16, v86
	v_pk_fma_f32 v[116:117], v[56:57], v[160:161], v[116:117] op_sel_hi:[1,0,1]
	v_pk_fma_f32 v[118:119], v[58:59], v[160:161], v[118:119] op_sel_hi:[1,0,1]
	v_lshlrev_b32_e32 v162, 16, v90
	v_pk_fma_f32 v[120:121], v[56:57], v[162:163], v[120:121] op_sel_hi:[1,0,1]
	v_pk_fma_f32 v[122:123], v[58:59], v[162:163], v[122:123] op_sel_hi:[1,0,1]
	v_lshlrev_b32_e32 v164, 16, v94
	v_pk_fma_f32 v[124:125], v[56:57], v[164:165], v[124:125] op_sel_hi:[1,0,1]
	v_pk_fma_f32 v[126:127], v[58:59], v[164:165], v[126:127] op_sel_hi:[1,0,1]
	v_lshlrev_b32_e32 v158, 16, v98
	v_pk_fma_f32 v[128:129], v[56:57], v[158:159], v[128:129] op_sel_hi:[1,0,1]
	v_pk_fma_f32 v[130:131], v[58:59], v[158:159], v[130:131] op_sel_hi:[1,0,1]
	v_lshlrev_b32_e32 v160, 16, v102
	v_pk_fma_f32 v[132:133], v[56:57], v[160:161], v[132:133] op_sel_hi:[1,0,1]
	v_pk_fma_f32 v[134:135], v[58:59], v[160:161], v[134:135] op_sel_hi:[1,0,1]
	v_lshlrev_b32_e32 v162, 16, v106
	v_pk_fma_f32 v[136:137], v[56:57], v[162:163], v[136:137] op_sel_hi:[1,0,1]
	v_pk_fma_f32 v[138:139], v[58:59], v[162:163], v[138:139] op_sel_hi:[1,0,1]
	v_lshlrev_b32_e32 v164, 16, v110
	v_pk_fma_f32 v[72:73], v[56:57], v[164:165], v[72:73] op_sel_hi:[1,0,1]
	v_pk_fma_f32 v[74:75], v[58:59], v[164:165], v[74:75] op_sel_hi:[1,0,1]
	v_mov_b32_e32 v166, v221
	v_pk_fma_f32 v[146:147], v[60:61], v[166:167], v[146:147] op_sel_hi:[1,0,1]
	v_pk_fma_f32 v[148:149], v[62:63], v[166:167], v[148:149] op_sel_hi:[1,0,1]
	v_and_b32_e32 v158, 0xffff0000, v82
	v_pk_fma_f32 v[112:113], v[60:61], v[158:159], v[112:113] op_sel_hi:[1,0,1]
	v_pk_fma_f32 v[114:115], v[62:63], v[158:159], v[114:115] op_sel_hi:[1,0,1]
	v_and_b32_e32 v160, 0xffff0000, v86
	v_pk_fma_f32 v[116:117], v[60:61], v[160:161], v[116:117] op_sel_hi:[1,0,1]
	v_pk_fma_f32 v[118:119], v[62:63], v[160:161], v[118:119] op_sel_hi:[1,0,1]
	v_and_b32_e32 v162, 0xffff0000, v90
	v_pk_fma_f32 v[120:121], v[60:61], v[162:163], v[120:121] op_sel_hi:[1,0,1]
	v_pk_fma_f32 v[122:123], v[62:63], v[162:163], v[122:123] op_sel_hi:[1,0,1]
	v_and_b32_e32 v164, 0xffff0000, v94
	v_pk_fma_f32 v[124:125], v[60:61], v[164:165], v[124:125] op_sel_hi:[1,0,1]
	v_pk_fma_f32 v[126:127], v[62:63], v[164:165], v[126:127] op_sel_hi:[1,0,1]
	v_and_b32_e32 v158, 0xffff0000, v98
	v_pk_fma_f32 v[128:129], v[60:61], v[158:159], v[128:129] op_sel_hi:[1,0,1]
	v_pk_fma_f32 v[130:131], v[62:63], v[158:159], v[130:131] op_sel_hi:[1,0,1]
	v_and_b32_e32 v160, 0xffff0000, v102
	v_pk_fma_f32 v[132:133], v[60:61], v[160:161], v[132:133] op_sel_hi:[1,0,1]
	v_pk_fma_f32 v[134:135], v[62:63], v[160:161], v[134:135] op_sel_hi:[1,0,1]
	v_and_b32_e32 v162, 0xffff0000, v106
	v_pk_fma_f32 v[136:137], v[60:61], v[162:163], v[136:137] op_sel_hi:[1,0,1]
	v_pk_fma_f32 v[138:139], v[62:63], v[162:163], v[138:139] op_sel_hi:[1,0,1]
	v_and_b32_e32 v164, 0xffff0000, v110
	v_pk_fma_f32 v[72:73], v[60:61], v[164:165], v[72:73] op_sel_hi:[1,0,1]
	v_pk_fma_f32 v[74:75], v[62:63], v[164:165], v[74:75] op_sel_hi:[1,0,1]
	v_pk_fma_f32 v[146:147], v[64:65], v[222:223], v[146:147] op_sel_hi:[1,0,1]
	v_pk_fma_f32 v[148:149], v[66:67], v[222:223], v[148:149] op_sel_hi:[1,0,1]
	v_lshlrev_b32_e32 v158, 16, v83
	v_pk_fma_f32 v[112:113], v[64:65], v[158:159], v[112:113] op_sel_hi:[1,0,1]
	v_pk_fma_f32 v[114:115], v[66:67], v[158:159], v[114:115] op_sel_hi:[1,0,1]
	v_lshlrev_b32_e32 v160, 16, v87
	v_pk_fma_f32 v[116:117], v[64:65], v[160:161], v[116:117] op_sel_hi:[1,0,1]
	v_pk_fma_f32 v[118:119], v[66:67], v[160:161], v[118:119] op_sel_hi:[1,0,1]
	v_lshlrev_b32_e32 v162, 16, v91
	v_pk_fma_f32 v[120:121], v[64:65], v[162:163], v[120:121] op_sel_hi:[1,0,1]
	v_pk_fma_f32 v[122:123], v[66:67], v[162:163], v[122:123] op_sel_hi:[1,0,1]
	v_lshlrev_b32_e32 v164, 16, v95
	v_pk_fma_f32 v[124:125], v[64:65], v[164:165], v[124:125] op_sel_hi:[1,0,1]
	v_pk_fma_f32 v[126:127], v[66:67], v[164:165], v[126:127] op_sel_hi:[1,0,1]
	v_lshlrev_b32_e32 v158, 16, v99
	v_pk_fma_f32 v[128:129], v[64:65], v[158:159], v[128:129] op_sel_hi:[1,0,1]
	v_pk_fma_f32 v[130:131], v[66:67], v[158:159], v[130:131] op_sel_hi:[1,0,1]
	v_lshlrev_b32_e32 v160, 16, v103
	v_pk_fma_f32 v[132:133], v[64:65], v[160:161], v[132:133] op_sel_hi:[1,0,1]
	v_pk_fma_f32 v[134:135], v[66:67], v[160:161], v[134:135] op_sel_hi:[1,0,1]
; DI float bf2f(bf16_t v) { return __uint_as_float(((unsigned)v) << 16); }
; DI f32x4 gldfv(const void* p) { f32x4 r; asm volatile("global_load_dwordx4 %0, %1, off" : "=v"(r) : "v"(p) : "memory"); return r; }
; DI void nsa_compress(const Params& p, int l, int item, char* smem) {
;     ...
;   for (int ib = 0; ib < 512; ib += 8) {
;     f32x4 wr[8];
; #pragma unroll
;     for (int u = 0; u < 8; ++u) wr[u] = gldfv(w1 + (size_t)(i0 + ib + u) * 256);
;     asm volatile("s_waitcnt vmcnt(0)" : "+v"(wr[0]), "+v"(wr[1]), "+v"(wr[2]), "+v"(wr[3]), "+v"(wr[4]), "+v"(wr[5]), "+v"(wr[6]), "+v"(wr[7]) :: "memory");
; #pragma unroll
;     for (int u = 0; u < 8; ++u) { const int i = i0 + ib + u, tk = i >> 6, d = i & 63; const float pv = pe[i]; const f32x4 w = wr[u];
;       bias[0] += pv * w[0]; bias[1] += pv * w[1]; bias[2] += pv * w[2]; bias[3] += pv * w[3];
; #pragma unroll
;       for (int r = 0; r < 8; ++r) { const float xv = bf2f(X[(16 * r + tk) * 64 + d]); acc[r][0] += xv * w[0]; acc[r][1] += xv * w[1]; acc[r][2] += xv * w[2]; acc[r][3] += xv * w[3]; } }
	v_lshlrev_b32_e32 v162, 16, v107
	v_pk_fma_f32 v[136:137], v[64:65], v[162:163], v[136:137] op_sel_hi:[1,0,1]
	v_pk_fma_f32 v[138:139], v[66:67], v[162:163], v[138:139] op_sel_hi:[1,0,1]
	v_lshlrev_b32_e32 v164, 16, v111
	v_pk_fma_f32 v[72:73], v[64:65], v[164:165], v[72:73] op_sel_hi:[1,0,1]
	v_pk_fma_f32 v[74:75], v[66:67], v[164:165], v[74:75] op_sel_hi:[1,0,1]
	v_mov_b32_e32 v166, v223
	v_pk_fma_f32 v[146:147], v[68:69], v[166:167], v[146:147] op_sel_hi:[1,0,1]
	v_pk_fma_f32 v[148:149], v[70:71], v[166:167], v[148:149] op_sel_hi:[1,0,1]
	v_and_b32_e32 v158, 0xffff0000, v83
	v_pk_fma_f32 v[112:113], v[68:69], v[158:159], v[112:113] op_sel_hi:[1,0,1]
	v_pk_fma_f32 v[114:115], v[70:71], v[158:159], v[114:115] op_sel_hi:[1,0,1]
	v_and_b32_e32 v160, 0xffff0000, v87
	v_pk_fma_f32 v[116:117], v[68:69], v[160:161], v[116:117] op_sel_hi:[1,0,1]
	v_pk_fma_f32 v[118:119], v[70:71], v[160:161], v[118:119] op_sel_hi:[1,0,1]
	v_and_b32_e32 v162, 0xffff0000, v91
	v_pk_fma_f32 v[120:121], v[68:69], v[162:163], v[120:121] op_sel_hi:[1,0,1]
	v_pk_fma_f32 v[122:123], v[70:71], v[162:163], v[122:123] op_sel_hi:[1,0,1]
	v_and_b32_e32 v164, 0xffff0000, v95
	v_pk_fma_f32 v[124:125], v[68:69], v[164:165], v[124:125] op_sel_hi:[1,0,1]
	v_pk_fma_f32 v[126:127], v[70:71], v[164:165], v[126:127] op_sel_hi:[1,0,1]
	v_and_b32_e32 v158, 0xffff0000, v99
	v_pk_fma_f32 v[128:129], v[68:69], v[158:159], v[128:129] op_sel_hi:[1,0,1]
	v_pk_fma_f32 v[130:131], v[70:71], v[158:159], v[130:131] op_sel_hi:[1,0,1]
	v_and_b32_e32 v160, 0xffff0000, v103
	v_pk_fma_f32 v[132:133], v[68:69], v[160:161], v[132:133] op_sel_hi:[1,0,1]
	v_pk_fma_f32 v[134:135], v[70:71], v[160:161], v[134:135] op_sel_hi:[1,0,1]
	v_and_b32_e32 v162, 0xffff0000, v107
	v_pk_fma_f32 v[136:137], v[68:69], v[162:163], v[136:137] op_sel_hi:[1,0,1]
	v_pk_fma_f32 v[138:139], v[70:71], v[162:163], v[138:139] op_sel_hi:[1,0,1]
	v_and_b32_e32 v164, 0xffff0000, v111
	v_pk_fma_f32 v[72:73], v[68:69], v[164:165], v[72:73] op_sel_hi:[1,0,1]
	v_pk_fma_f32 v[74:75], v[70:71], v[164:165], v[74:75] op_sel_hi:[1,0,1]
	s_add_i32 s2, s2, 1
	s_cmp_lt_u32 s2, 31
	s_cbranch_scc1 .Lcmp_loop
	global_load_dwordx4 v[40:43], v[202:203], off
	global_load_dwordx4 v[44:47], v[202:203], off offset:1024
	global_load_dwordx4 v[48:51], v[202:203], off offset:2048
	global_load_dwordx4 v[52:55], v[202:203], off offset:3072
	global_load_dwordx4 v[56:59], v[204:205], off
	global_load_dwordx4 v[60:63], v[204:205], off offset:1024
	global_load_dwordx4 v[64:67], v[204:205], off offset:2048
	global_load_dwordx4 v[68:71], v[204:205], off offset:3072
	global_load_dwordx4 v[216:219], v[206:207], off offset:-28
	global_load_dwordx4 v[220:223], v[206:207], off offset:-12
	v_lshl_add_u64 v[202:203], v[202:203], 0, s[12:13]
	v_lshl_add_u64 v[204:205], v[204:205], 0, s[12:13]
	v_lshl_add_u64 v[206:207], v[206:207], 0, 32
	ds_read_b128 v[80:83], v208
	ds_read_b128 v[84:87], v208 offset:2048
	ds_read_b128 v[88:91], v208 offset:4096
	ds_read_b128 v[92:95], v208 offset:6144
	ds_read_b128 v[96:99], v208 offset:8192
	ds_read_b128 v[100:103], v208 offset:10240
	ds_read_b128 v[104:107], v208 offset:12288
	ds_read_b128 v[108:111], v208 offset:14336
	v_add_u32_e32 v208, 16, v208
	s_waitcnt vmcnt(10)
	s_waitcnt lgkmcnt(0)
	v_pk_fma_f32 v[146:147], v[0:1], v[150:151], v[146:147] op_sel_hi:[1,0,1]
	v_pk_fma_f32 v[148:149], v[2:3], v[150:151], v[148:149] op_sel_hi:[1,0,1]
	v_lshlrev_b32_e32 v158, 16, v80
	v_pk_fma_f32 v[112:113], v[0:1], v[158:159], v[112:113] op_sel_hi:[1,0,1]
	v_pk_fma_f32 v[114:115], v[2:3], v[158:159], v[114:115] op_sel_hi:[1,0,1]
	v_lshlrev_b32_e32 v160, 16, v84
	v_pk_fma_f32 v[116:117], v[0:1], v[160:161], v[116:117] op_sel_hi:[1,0,1]
	v_pk_fma_f32 v[118:119], v[2:3], v[160:161], v[118:119] op_sel_hi:[1,0,1]
	v_lshlrev_b32_e32 v162, 16, v88
	v_pk_fma_f32 v[120:121], v[0:1], v[162:163], v[120:121] op_sel_hi:[1,0,1]
	v_pk_fma_f32 v[122:123], v[2:3], v[162:163], v[122:123] op_sel_hi:[1,0,1]
	v_lshlrev_b32_e32 v164, 16, v92
	v_pk_fma_f32 v[124:125], v[0:1], v[164:165], v[124:125] op_sel_hi:[1,0,1]
	v_pk_fma_f32 v[126:127], v[2:3], v[164:165], v[126:127] op_sel_hi:[1,0,1]
	v_lshlrev_b32_e32 v158, 16, v96
	v_pk_fma_f32 v[128:129], v[0:1], v[158:159], v[128:129] op_sel_hi:[1,0,1]
	v_pk_fma_f32 v[130:131], v[2:3], v[158:159], v[130:131] op_sel_hi:[1,0,1]
	v_lshlrev_b32_e32 v160, 16, v100
	v_pk_fma_f32 v[132:133], v[0:1], v[160:161], v[132:133] op_sel_hi:[1,0,1]
	v_pk_fma_f32 v[134:135], v[2:3], v[160:161], v[134:135] op_sel_hi:[1,0,1]
	v_lshlrev_b32_e32 v162, 16, v104
	v_pk_fma_f32 v[136:137], v[0:1], v[162:163], v[136:137] op_sel_hi:[1,0,1]
	v_pk_fma_f32 v[138:139], v[2:3], v[162:163], v[138:139] op_sel_hi:[1,0,1]
	v_lshlrev_b32_e32 v164, 16, v108
	v_pk_fma_f32 v[72:73], v[0:1], v[164:165], v[72:73] op_sel_hi:[1,0,1]
	v_pk_fma_f32 v[74:75], v[2:3], v[164:165], v[74:75] op_sel_hi:[1,0,1]
	v_mov_b32_e32 v166, v151
	v_pk_fma_f32 v[146:147], v[4:5], v[166:167], v[146:147] op_sel_hi:[1,0,1]
	v_pk_fma_f32 v[148:149], v[6:7], v[166:167], v[148:149] op_sel_hi:[1,0,1]
	v_and_b32_e32 v158, 0xffff0000, v80
	v_pk_fma_f32 v[112:113], v[4:5], v[158:159], v[112:113] op_sel_hi:[1,0,1]
	v_pk_fma_f32 v[114:115], v[6:7], v[158:159], v[114:115] op_sel_hi:[1,0,1]
	v_and_b32_e32 v160, 0xffff0000, v84
	v_pk_fma_f32 v[116:117], v[4:5], v[160:161], v[116:117] op_sel_hi:[1,0,1]
	v_pk_fma_f32 v[118:119], v[6:7], v[160:161], v[118:119] op_sel_hi:[1,0,1]
	v_and_b32_e32 v162, 0xffff0000, v88
	v_pk_fma_f32 v[120:121], v[4:5], v[162:163], v[120:121] op_sel_hi:[1,0,1]
	v_pk_fma_f32 v[122:123], v[6:7], v[162:163], v[122:123] op_sel_hi:[1,0,1]
	v_and_b32_e32 v164, 0xffff0000, v92
; DI float bf2f(bf16_t v) { return __uint_as_float(((unsigned)v) << 16); }
; DI void nsa_compress(const Params& p, int l, int item, char* smem) {
;     ...
;     for (int u = 0; u < 8; ++u) { const int i = i0 + ib + u, tk = i >> 6, d = i & 63; const float pv = pe[i]; const f32x4 w = wr[u];
;       bias[0] += pv * w[0]; bias[1] += pv * w[1]; bias[2] += pv * w[2]; bias[3] += pv * w[3];
; #pragma unroll
;       for (int r = 0; r < 8; ++r) { const float xv = bf2f(X[(16 * r + tk) * 64 + d]); acc[r][0] += xv * w[0]; acc[r][1] += xv * w[1]; acc[r][2] += xv * w[2]; acc[r][3] += xv * w[3]; } }
	v_pk_fma_f32 v[124:125], v[4:5], v[164:165], v[124:125] op_sel_hi:[1,0,1]
	v_pk_fma_f32 v[126:127], v[6:7], v[164:165], v[126:127] op_sel_hi:[1,0,1]
	v_and_b32_e32 v158, 0xffff0000, v96
	v_pk_fma_f32 v[128:129], v[4:5], v[158:159], v[128:129] op_sel_hi:[1,0,1]
	v_pk_fma_f32 v[130:131], v[6:7], v[158:159], v[130:131] op_sel_hi:[1,0,1]
	v_and_b32_e32 v160, 0xffff0000, v100
	v_pk_fma_f32 v[132:133], v[4:5], v[160:161], v[132:133] op_sel_hi:[1,0,1]
	v_pk_fma_f32 v[134:135], v[6:7], v[160:161], v[134:135] op_sel_hi:[1,0,1]
	v_and_b32_e32 v162, 0xffff0000, v104
	v_pk_fma_f32 v[136:137], v[4:5], v[162:163], v[136:137] op_sel_hi:[1,0,1]
	v_pk_fma_f32 v[138:139], v[6:7], v[162:163], v[138:139] op_sel_hi:[1,0,1]
	v_and_b32_e32 v164, 0xffff0000, v108
	v_pk_fma_f32 v[72:73], v[4:5], v[164:165], v[72:73] op_sel_hi:[1,0,1]
	v_pk_fma_f32 v[74:75], v[6:7], v[164:165], v[74:75] op_sel_hi:[1,0,1]
	v_pk_fma_f32 v[146:147], v[8:9], v[152:153], v[146:147] op_sel_hi:[1,0,1]
	v_pk_fma_f32 v[148:149], v[10:11], v[152:153], v[148:149] op_sel_hi:[1,0,1]
	v_lshlrev_b32_e32 v158, 16, v81
	v_pk_fma_f32 v[112:113], v[8:9], v[158:159], v[112:113] op_sel_hi:[1,0,1]
	v_pk_fma_f32 v[114:115], v[10:11], v[158:159], v[114:115] op_sel_hi:[1,0,1]
	v_lshlrev_b32_e32 v160, 16, v85
	v_pk_fma_f32 v[116:117], v[8:9], v[160:161], v[116:117] op_sel_hi:[1,0,1]
	v_pk_fma_f32 v[118:119], v[10:11], v[160:161], v[118:119] op_sel_hi:[1,0,1]
	v_lshlrev_b32_e32 v162, 16, v89
	v_pk_fma_f32 v[120:121], v[8:9], v[162:163], v[120:121] op_sel_hi:[1,0,1]
	v_pk_fma_f32 v[122:123], v[10:11], v[162:163], v[122:123] op_sel_hi:[1,0,1]
	v_lshlrev_b32_e32 v164, 16, v93
	v_pk_fma_f32 v[124:125], v[8:9], v[164:165], v[124:125] op_sel_hi:[1,0,1]
	v_pk_fma_f32 v[126:127], v[10:11], v[164:165], v[126:127] op_sel_hi:[1,0,1]
	v_lshlrev_b32_e32 v158, 16, v97
	v_pk_fma_f32 v[128:129], v[8:9], v[158:159], v[128:129] op_sel_hi:[1,0,1]
	v_pk_fma_f32 v[130:131], v[10:11], v[158:159], v[130:131] op_sel_hi:[1,0,1]
	v_lshlrev_b32_e32 v160, 16, v101
	v_pk_fma_f32 v[132:133], v[8:9], v[160:161], v[132:133] op_sel_hi:[1,0,1]
	v_pk_fma_f32 v[134:135], v[10:11], v[160:161], v[134:135] op_sel_hi:[1,0,1]
	v_lshlrev_b32_e32 v162, 16, v105
	v_pk_fma_f32 v[136:137], v[8:9], v[162:163], v[136:137] op_sel_hi:[1,0,1]
	v_pk_fma_f32 v[138:139], v[10:11], v[162:163], v[138:139] op_sel_hi:[1,0,1]
	v_lshlrev_b32_e32 v164, 16, v109
	v_pk_fma_f32 v[72:73], v[8:9], v[164:165], v[72:73] op_sel_hi:[1,0,1]
	v_pk_fma_f32 v[74:75], v[10:11], v[164:165], v[74:75] op_sel_hi:[1,0,1]
	v_mov_b32_e32 v166, v153
	v_pk_fma_f32 v[146:147], v[12:13], v[166:167], v[146:147] op_sel_hi:[1,0,1]
	v_pk_fma_f32 v[148:149], v[14:15], v[166:167], v[148:149] op_sel_hi:[1,0,1]
	v_and_b32_e32 v158, 0xffff0000, v81
	v_pk_fma_f32 v[112:113], v[12:13], v[158:159], v[112:113] op_sel_hi:[1,0,1]
	v_pk_fma_f32 v[114:115], v[14:15], v[158:159], v[114:115] op_sel_hi:[1,0,1]
	v_and_b32_e32 v160, 0xffff0000, v85
	v_pk_fma_f32 v[116:117], v[12:13], v[160:161], v[116:117] op_sel_hi:[1,0,1]
	v_pk_fma_f32 v[118:119], v[14:15], v[160:161], v[118:119] op_sel_hi:[1,0,1]
	v_and_b32_e32 v162, 0xffff0000, v89
	v_pk_fma_f32 v[120:121], v[12:13], v[162:163], v[120:121] op_sel_hi:[1,0,1]
	v_pk_fma_f32 v[122:123], v[14:15], v[162:163], v[122:123] op_sel_hi:[1,0,1]
	v_and_b32_e32 v164, 0xffff0000, v93
	v_pk_fma_f32 v[124:125], v[12:13], v[164:165], v[124:125] op_sel_hi:[1,0,1]
	v_pk_fma_f32 v[126:127], v[14:15], v[164:165], v[126:127] op_sel_hi:[1,0,1]
	v_and_b32_e32 v158, 0xffff0000, v97
	v_pk_fma_f32 v[128:129], v[12:13], v[158:159], v[128:129] op_sel_hi:[1,0,1]
	v_pk_fma_f32 v[130:131], v[14:15], v[158:159], v[130:131] op_sel_hi:[1,0,1]
	v_and_b32_e32 v160, 0xffff0000, v101
	v_pk_fma_f32 v[132:133], v[12:13], v[160:161], v[132:133] op_sel_hi:[1,0,1]
	v_pk_fma_f32 v[134:135], v[14:15], v[160:161], v[134:135] op_sel_hi:[1,0,1]
	v_and_b32_e32 v162, 0xffff0000, v105
	v_pk_fma_f32 v[136:137], v[12:13], v[162:163], v[136:137] op_sel_hi:[1,0,1]
	v_pk_fma_f32 v[138:139], v[14:15], v[162:163], v[138:139] op_sel_hi:[1,0,1]
	v_and_b32_e32 v164, 0xffff0000, v109
	v_pk_fma_f32 v[72:73], v[12:13], v[164:165], v[72:73] op_sel_hi:[1,0,1]
	v_pk_fma_f32 v[74:75], v[14:15], v[164:165], v[74:75] op_sel_hi:[1,0,1]
	v_pk_fma_f32 v[146:147], v[16:17], v[154:155], v[146:147] op_sel_hi:[1,0,1]
	v_pk_fma_f32 v[148:149], v[18:19], v[154:155], v[148:149] op_sel_hi:[1,0,1]
	v_lshlrev_b32_e32 v158, 16, v82
	v_pk_fma_f32 v[112:113], v[16:17], v[158:159], v[112:113] op_sel_hi:[1,0,1]
	v_pk_fma_f32 v[114:115], v[18:19], v[158:159], v[114:115] op_sel_hi:[1,0,1]
	v_lshlrev_b32_e32 v160, 16, v86
	v_pk_fma_f32 v[116:117], v[16:17], v[160:161], v[116:117] op_sel_hi:[1,0,1]
	v_pk_fma_f32 v[118:119], v[18:19], v[160:161], v[118:119] op_sel_hi:[1,0,1]
	v_lshlrev_b32_e32 v162, 16, v90
	v_pk_fma_f32 v[120:121], v[16:17], v[162:163], v[120:121] op_sel_hi:[1,0,1]
	v_pk_fma_f32 v[122:123], v[18:19], v[162:163], v[122:123] op_sel_hi:[1,0,1]
	v_lshlrev_b32_e32 v164, 16, v94
	v_pk_fma_f32 v[124:125], v[16:17], v[164:165], v[124:125] op_sel_hi:[1,0,1]
	v_pk_fma_f32 v[126:127], v[18:19], v[164:165], v[126:127] op_sel_hi:[1,0,1]
	v_lshlrev_b32_e32 v158, 16, v98
	v_pk_fma_f32 v[128:129], v[16:17], v[158:159], v[128:129] op_sel_hi:[1,0,1]
	v_pk_fma_f32 v[130:131], v[18:19], v[158:159], v[130:131] op_sel_hi:[1,0,1]
	v_lshlrev_b32_e32 v160, 16, v102
	v_pk_fma_f32 v[132:133], v[16:17], v[160:161], v[132:133] op_sel_hi:[1,0,1]
	v_pk_fma_f32 v[134:135], v[18:19], v[160:161], v[134:135] op_sel_hi:[1,0,1]
	v_lshlrev_b32_e32 v162, 16, v106
	v_pk_fma_f32 v[136:137], v[16:17], v[162:163], v[136:137] op_sel_hi:[1,0,1]
; DI float bf2f(bf16_t v) { return __uint_as_float(((unsigned)v) << 16); }
; DI f32x4 gldfv(const void* p) { f32x4 r; asm volatile("global_load_dwordx4 %0, %1, off" : "=v"(r) : "v"(p) : "memory"); return r; }
; DI void nsa_compress(const Params& p, int l, int item, char* smem) {
;     ...
;   for (int ib = 0; ib < 512; ib += 8) {
;     f32x4 wr[8];
; #pragma unroll
;     for (int u = 0; u < 8; ++u) wr[u] = gldfv(w1 + (size_t)(i0 + ib + u) * 256);
;     asm volatile("s_waitcnt vmcnt(0)" : "+v"(wr[0]), "+v"(wr[1]), "+v"(wr[2]), "+v"(wr[3]), "+v"(wr[4]), "+v"(wr[5]), "+v"(wr[6]), "+v"(wr[7]) :: "memory");
; #pragma unroll
;     for (int u = 0; u < 8; ++u) { const int i = i0 + ib + u, tk = i >> 6, d = i & 63; const float pv = pe[i]; const f32x4 w = wr[u];
;       bias[0] += pv * w[0]; bias[1] += pv * w[1]; bias[2] += pv * w[2]; bias[3] += pv * w[3];
; #pragma unroll
;       for (int r = 0; r < 8; ++r) { const float xv = bf2f(X[(16 * r + tk) * 64 + d]); acc[r][0] += xv * w[0]; acc[r][1] += xv * w[1]; acc[r][2] += xv * w[2]; acc[r][3] += xv * w[3]; } }
	v_pk_fma_f32 v[138:139], v[18:19], v[162:163], v[138:139] op_sel_hi:[1,0,1]
	v_lshlrev_b32_e32 v164, 16, v110
	v_pk_fma_f32 v[72:73], v[16:17], v[164:165], v[72:73] op_sel_hi:[1,0,1]
	v_pk_fma_f32 v[74:75], v[18:19], v[164:165], v[74:75] op_sel_hi:[1,0,1]
	v_mov_b32_e32 v166, v155
	v_pk_fma_f32 v[146:147], v[20:21], v[166:167], v[146:147] op_sel_hi:[1,0,1]
	v_pk_fma_f32 v[148:149], v[22:23], v[166:167], v[148:149] op_sel_hi:[1,0,1]
	v_and_b32_e32 v158, 0xffff0000, v82
	v_pk_fma_f32 v[112:113], v[20:21], v[158:159], v[112:113] op_sel_hi:[1,0,1]
	v_pk_fma_f32 v[114:115], v[22:23], v[158:159], v[114:115] op_sel_hi:[1,0,1]
	v_and_b32_e32 v160, 0xffff0000, v86
	v_pk_fma_f32 v[116:117], v[20:21], v[160:161], v[116:117] op_sel_hi:[1,0,1]
	v_pk_fma_f32 v[118:119], v[22:23], v[160:161], v[118:119] op_sel_hi:[1,0,1]
	v_and_b32_e32 v162, 0xffff0000, v90
	v_pk_fma_f32 v[120:121], v[20:21], v[162:163], v[120:121] op_sel_hi:[1,0,1]
	v_pk_fma_f32 v[122:123], v[22:23], v[162:163], v[122:123] op_sel_hi:[1,0,1]
	v_and_b32_e32 v164, 0xffff0000, v94
	v_pk_fma_f32 v[124:125], v[20:21], v[164:165], v[124:125] op_sel_hi:[1,0,1]
	v_pk_fma_f32 v[126:127], v[22:23], v[164:165], v[126:127] op_sel_hi:[1,0,1]
	v_and_b32_e32 v158, 0xffff0000, v98
	v_pk_fma_f32 v[128:129], v[20:21], v[158:159], v[128:129] op_sel_hi:[1,0,1]
	v_pk_fma_f32 v[130:131], v[22:23], v[158:159], v[130:131] op_sel_hi:[1,0,1]
	v_and_b32_e32 v160, 0xffff0000, v102
	v_pk_fma_f32 v[132:133], v[20:21], v[160:161], v[132:133] op_sel_hi:[1,0,1]
	v_pk_fma_f32 v[134:135], v[22:23], v[160:161], v[134:135] op_sel_hi:[1,0,1]
	v_and_b32_e32 v162, 0xffff0000, v106
	v_pk_fma_f32 v[136:137], v[20:21], v[162:163], v[136:137] op_sel_hi:[1,0,1]
	v_pk_fma_f32 v[138:139], v[22:23], v[162:163], v[138:139] op_sel_hi:[1,0,1]
	v_and_b32_e32 v164, 0xffff0000, v110
	v_pk_fma_f32 v[72:73], v[20:21], v[164:165], v[72:73] op_sel_hi:[1,0,1]
	v_pk_fma_f32 v[74:75], v[22:23], v[164:165], v[74:75] op_sel_hi:[1,0,1]
	v_pk_fma_f32 v[146:147], v[24:25], v[156:157], v[146:147] op_sel_hi:[1,0,1]
	v_pk_fma_f32 v[148:149], v[26:27], v[156:157], v[148:149] op_sel_hi:[1,0,1]
	v_lshlrev_b32_e32 v158, 16, v83
	v_pk_fma_f32 v[112:113], v[24:25], v[158:159], v[112:113] op_sel_hi:[1,0,1]
	v_pk_fma_f32 v[114:115], v[26:27], v[158:159], v[114:115] op_sel_hi:[1,0,1]
	v_lshlrev_b32_e32 v160, 16, v87
	v_pk_fma_f32 v[116:117], v[24:25], v[160:161], v[116:117] op_sel_hi:[1,0,1]
	v_pk_fma_f32 v[118:119], v[26:27], v[160:161], v[118:119] op_sel_hi:[1,0,1]
	v_lshlrev_b32_e32 v162, 16, v91
	v_pk_fma_f32 v[120:121], v[24:25], v[162:163], v[120:121] op_sel_hi:[1,0,1]
	v_pk_fma_f32 v[122:123], v[26:27], v[162:163], v[122:123] op_sel_hi:[1,0,1]
	v_lshlrev_b32_e32 v164, 16, v95
	v_pk_fma_f32 v[124:125], v[24:25], v[164:165], v[124:125] op_sel_hi:[1,0,1]
	v_pk_fma_f32 v[126:127], v[26:27], v[164:165], v[126:127] op_sel_hi:[1,0,1]
	v_lshlrev_b32_e32 v158, 16, v99
	v_pk_fma_f32 v[128:129], v[24:25], v[158:159], v[128:129] op_sel_hi:[1,0,1]
	v_pk_fma_f32 v[130:131], v[26:27], v[158:159], v[130:131] op_sel_hi:[1,0,1]
	v_lshlrev_b32_e32 v160, 16, v103
	v_pk_fma_f32 v[132:133], v[24:25], v[160:161], v[132:133] op_sel_hi:[1,0,1]
	v_pk_fma_f32 v[134:135], v[26:27], v[160:161], v[134:135] op_sel_hi:[1,0,1]
	v_lshlrev_b32_e32 v162, 16, v107
	v_pk_fma_f32 v[136:137], v[24:25], v[162:163], v[136:137] op_sel_hi:[1,0,1]
	v_pk_fma_f32 v[138:139], v[26:27], v[162:163], v[138:139] op_sel_hi:[1,0,1]
	v_lshlrev_b32_e32 v164, 16, v111
	v_pk_fma_f32 v[72:73], v[24:25], v[164:165], v[72:73] op_sel_hi:[1,0,1]
	v_pk_fma_f32 v[74:75], v[26:27], v[164:165], v[74:75] op_sel_hi:[1,0,1]
	v_mov_b32_e32 v166, v157
	v_pk_fma_f32 v[146:147], v[28:29], v[166:167], v[146:147] op_sel_hi:[1,0,1]
	v_pk_fma_f32 v[148:149], v[30:31], v[166:167], v[148:149] op_sel_hi:[1,0,1]
	v_and_b32_e32 v158, 0xffff0000, v83
	v_pk_fma_f32 v[112:113], v[28:29], v[158:159], v[112:113] op_sel_hi:[1,0,1]
	v_pk_fma_f32 v[114:115], v[30:31], v[158:159], v[114:115] op_sel_hi:[1,0,1]
	v_and_b32_e32 v160, 0xffff0000, v87
	v_pk_fma_f32 v[116:117], v[28:29], v[160:161], v[116:117] op_sel_hi:[1,0,1]
	v_pk_fma_f32 v[118:119], v[30:31], v[160:161], v[118:119] op_sel_hi:[1,0,1]
	v_and_b32_e32 v162, 0xffff0000, v91
	v_pk_fma_f32 v[120:121], v[28:29], v[162:163], v[120:121] op_sel_hi:[1,0,1]
	v_pk_fma_f32 v[122:123], v[30:31], v[162:163], v[122:123] op_sel_hi:[1,0,1]
	v_and_b32_e32 v164, 0xffff0000, v95
	v_pk_fma_f32 v[124:125], v[28:29], v[164:165], v[124:125] op_sel_hi:[1,0,1]
	v_pk_fma_f32 v[126:127], v[30:31], v[164:165], v[126:127] op_sel_hi:[1,0,1]
	v_and_b32_e32 v158, 0xffff0000, v99
	v_pk_fma_f32 v[128:129], v[28:29], v[158:159], v[128:129] op_sel_hi:[1,0,1]
	v_pk_fma_f32 v[130:131], v[30:31], v[158:159], v[130:131] op_sel_hi:[1,0,1]
	v_and_b32_e32 v160, 0xffff0000, v103
	v_pk_fma_f32 v[132:133], v[28:29], v[160:161], v[132:133] op_sel_hi:[1,0,1]
	v_pk_fma_f32 v[134:135], v[30:31], v[160:161], v[134:135] op_sel_hi:[1,0,1]
	v_and_b32_e32 v162, 0xffff0000, v107
	v_pk_fma_f32 v[136:137], v[28:29], v[162:163], v[136:137] op_sel_hi:[1,0,1]
	v_pk_fma_f32 v[138:139], v[30:31], v[162:163], v[138:139] op_sel_hi:[1,0,1]
	v_and_b32_e32 v164, 0xffff0000, v111
	v_pk_fma_f32 v[72:73], v[28:29], v[164:165], v[72:73] op_sel_hi:[1,0,1]
	v_pk_fma_f32 v[74:75], v[30:31], v[164:165], v[74:75] op_sel_hi:[1,0,1]
	ds_read_b128 v[80:83], v208
	ds_read_b128 v[84:87], v208 offset:2048
	ds_read_b128 v[88:91], v208 offset:4096
	ds_read_b128 v[92:95], v208 offset:6144
	ds_read_b128 v[96:99], v208 offset:8192
	ds_read_b128 v[100:103], v208 offset:10240
	ds_read_b128 v[104:107], v208 offset:12288
	ds_read_b128 v[108:111], v208 offset:14336
	v_add_u32_e32 v208, 16, v208
	s_waitcnt vmcnt(0)
; DI float bf2f(bf16_t v) { return __uint_as_float(((unsigned)v) << 16); }
; DI f32x4 gldfv(const void* p) { f32x4 r; asm volatile("global_load_dwordx4 %0, %1, off" : "=v"(r) : "v"(p) : "memory"); return r; }
; DI void nsa_compress(const Params& p, int l, int item, char* smem) {
;     ...
;   for (int ib = 0; ib < 512; ib += 8) {
;     f32x4 wr[8];
; #pragma unroll
;     for (int u = 0; u < 8; ++u) wr[u] = gldfv(w1 + (size_t)(i0 + ib + u) * 256);
;     asm volatile("s_waitcnt vmcnt(0)" : "+v"(wr[0]), "+v"(wr[1]), "+v"(wr[2]), "+v"(wr[3]), "+v"(wr[4]), "+v"(wr[5]), "+v"(wr[6]), "+v"(wr[7]) :: "memory");
; #pragma unroll
;     for (int u = 0; u < 8; ++u) { const int i = i0 + ib + u, tk = i >> 6, d = i & 63; const float pv = pe[i]; const f32x4 w = wr[u];
;       bias[0] += pv * w[0]; bias[1] += pv * w[1]; bias[2] += pv * w[2]; bias[3] += pv * w[3];
; #pragma unroll
;       for (int r = 0; r < 8; ++r) { const float xv = bf2f(X[(16 * r + tk) * 64 + d]); acc[r][0] += xv * w[0]; acc[r][1] += xv * w[1]; acc[r][2] += xv * w[2]; acc[r][3] += xv * w[3]; } }
;   }
	s_waitcnt lgkmcnt(0)
	v_pk_fma_f32 v[146:147], v[40:41], v[216:217], v[146:147] op_sel_hi:[1,0,1]
	v_pk_fma_f32 v[148:149], v[42:43], v[216:217], v[148:149] op_sel_hi:[1,0,1]
	v_lshlrev_b32_e32 v158, 16, v80
	v_pk_fma_f32 v[112:113], v[40:41], v[158:159], v[112:113] op_sel_hi:[1,0,1]
	v_pk_fma_f32 v[114:115], v[42:43], v[158:159], v[114:115] op_sel_hi:[1,0,1]
	v_lshlrev_b32_e32 v160, 16, v84
	v_pk_fma_f32 v[116:117], v[40:41], v[160:161], v[116:117] op_sel_hi:[1,0,1]
	v_pk_fma_f32 v[118:119], v[42:43], v[160:161], v[118:119] op_sel_hi:[1,0,1]
	v_lshlrev_b32_e32 v162, 16, v88
	v_pk_fma_f32 v[120:121], v[40:41], v[162:163], v[120:121] op_sel_hi:[1,0,1]
	v_pk_fma_f32 v[122:123], v[42:43], v[162:163], v[122:123] op_sel_hi:[1,0,1]
	v_lshlrev_b32_e32 v164, 16, v92
	v_pk_fma_f32 v[124:125], v[40:41], v[164:165], v[124:125] op_sel_hi:[1,0,1]
	v_pk_fma_f32 v[126:127], v[42:43], v[164:165], v[126:127] op_sel_hi:[1,0,1]
	v_lshlrev_b32_e32 v158, 16, v96
	v_pk_fma_f32 v[128:129], v[40:41], v[158:159], v[128:129] op_sel_hi:[1,0,1]
	v_pk_fma_f32 v[130:131], v[42:43], v[158:159], v[130:131] op_sel_hi:[1,0,1]
	v_lshlrev_b32_e32 v160, 16, v100
	v_pk_fma_f32 v[132:133], v[40:41], v[160:161], v[132:133] op_sel_hi:[1,0,1]
	v_pk_fma_f32 v[134:135], v[42:43], v[160:161], v[134:135] op_sel_hi:[1,0,1]
	v_lshlrev_b32_e32 v162, 16, v104
	v_pk_fma_f32 v[136:137], v[40:41], v[162:163], v[136:137] op_sel_hi:[1,0,1]
	v_pk_fma_f32 v[138:139], v[42:43], v[162:163], v[138:139] op_sel_hi:[1,0,1]
	v_lshlrev_b32_e32 v164, 16, v108
	v_pk_fma_f32 v[72:73], v[40:41], v[164:165], v[72:73] op_sel_hi:[1,0,1]
	v_pk_fma_f32 v[74:75], v[42:43], v[164:165], v[74:75] op_sel_hi:[1,0,1]
	v_mov_b32_e32 v166, v217
	v_pk_fma_f32 v[146:147], v[44:45], v[166:167], v[146:147] op_sel_hi:[1,0,1]
	v_pk_fma_f32 v[148:149], v[46:47], v[166:167], v[148:149] op_sel_hi:[1,0,1]
	v_and_b32_e32 v158, 0xffff0000, v80
	v_pk_fma_f32 v[112:113], v[44:45], v[158:159], v[112:113] op_sel_hi:[1,0,1]
	v_pk_fma_f32 v[114:115], v[46:47], v[158:159], v[114:115] op_sel_hi:[1,0,1]
	v_and_b32_e32 v160, 0xffff0000, v84
	v_pk_fma_f32 v[116:117], v[44:45], v[160:161], v[116:117] op_sel_hi:[1,0,1]
	v_pk_fma_f32 v[118:119], v[46:47], v[160:161], v[118:119] op_sel_hi:[1,0,1]
	v_and_b32_e32 v162, 0xffff0000, v88
	v_pk_fma_f32 v[120:121], v[44:45], v[162:163], v[120:121] op_sel_hi:[1,0,1]
	v_pk_fma_f32 v[122:123], v[46:47], v[162:163], v[122:123] op_sel_hi:[1,0,1]
	v_and_b32_e32 v164, 0xffff0000, v92
	v_pk_fma_f32 v[124:125], v[44:45], v[164:165], v[124:125] op_sel_hi:[1,0,1]
	v_pk_fma_f32 v[126:127], v[46:47], v[164:165], v[126:127] op_sel_hi:[1,0,1]
	v_and_b32_e32 v158, 0xffff0000, v96
	v_pk_fma_f32 v[128:129], v[44:45], v[158:159], v[128:129] op_sel_hi:[1,0,1]
	v_pk_fma_f32 v[130:131], v[46:47], v[158:159], v[130:131] op_sel_hi:[1,0,1]
	v_and_b32_e32 v160, 0xffff0000, v100
	v_pk_fma_f32 v[132:133], v[44:45], v[160:161], v[132:133] op_sel_hi:[1,0,1]
	v_pk_fma_f32 v[134:135], v[46:47], v[160:161], v[134:135] op_sel_hi:[1,0,1]
	v_and_b32_e32 v162, 0xffff0000, v104
	v_pk_fma_f32 v[136:137], v[44:45], v[162:163], v[136:137] op_sel_hi:[1,0,1]
	v_pk_fma_f32 v[138:139], v[46:47], v[162:163], v[138:139] op_sel_hi:[1,0,1]
	v_and_b32_e32 v164, 0xffff0000, v108
	v_pk_fma_f32 v[72:73], v[44:45], v[164:165], v[72:73] op_sel_hi:[1,0,1]
	v_pk_fma_f32 v[74:75], v[46:47], v[164:165], v[74:75] op_sel_hi:[1,0,1]
	v_pk_fma_f32 v[146:147], v[48:49], v[218:219], v[146:147] op_sel_hi:[1,0,1]
	v_pk_fma_f32 v[148:149], v[50:51], v[218:219], v[148:149] op_sel_hi:[1,0,1]
	v_lshlrev_b32_e32 v158, 16, v81
	v_pk_fma_f32 v[112:113], v[48:49], v[158:159], v[112:113] op_sel_hi:[1,0,1]
	v_pk_fma_f32 v[114:115], v[50:51], v[158:159], v[114:115] op_sel_hi:[1,0,1]
	v_lshlrev_b32_e32 v160, 16, v85
	v_pk_fma_f32 v[116:117], v[48:49], v[160:161], v[116:117] op_sel_hi:[1,0,1]
	v_pk_fma_f32 v[118:119], v[50:51], v[160:161], v[118:119] op_sel_hi:[1,0,1]
	v_lshlrev_b32_e32 v162, 16, v89
	v_pk_fma_f32 v[120:121], v[48:49], v[162:163], v[120:121] op_sel_hi:[1,0,1]
	v_pk_fma_f32 v[122:123], v[50:51], v[162:163], v[122:123] op_sel_hi:[1,0,1]
	v_lshlrev_b32_e32 v164, 16, v93
	v_pk_fma_f32 v[124:125], v[48:49], v[164:165], v[124:125] op_sel_hi:[1,0,1]
	v_pk_fma_f32 v[126:127], v[50:51], v[164:165], v[126:127] op_sel_hi:[1,0,1]
	v_lshlrev_b32_e32 v158, 16, v97
	v_pk_fma_f32 v[128:129], v[48:49], v[158:159], v[128:129] op_sel_hi:[1,0,1]
	v_pk_fma_f32 v[130:131], v[50:51], v[158:159], v[130:131] op_sel_hi:[1,0,1]
	v_lshlrev_b32_e32 v160, 16, v101
	v_pk_fma_f32 v[132:133], v[48:49], v[160:161], v[132:133] op_sel_hi:[1,0,1]
	v_pk_fma_f32 v[134:135], v[50:51], v[160:161], v[134:135] op_sel_hi:[1,0,1]
	v_lshlrev_b32_e32 v162, 16, v105
	v_pk_fma_f32 v[136:137], v[48:49], v[162:163], v[136:137] op_sel_hi:[1,0,1]
	v_pk_fma_f32 v[138:139], v[50:51], v[162:163], v[138:139] op_sel_hi:[1,0,1]
	v_lshlrev_b32_e32 v164, 16, v109
	v_pk_fma_f32 v[72:73], v[48:49], v[164:165], v[72:73] op_sel_hi:[1,0,1]
	v_pk_fma_f32 v[74:75], v[50:51], v[164:165], v[74:75] op_sel_hi:[1,0,1]
	v_mov_b32_e32 v166, v219
	v_pk_fma_f32 v[146:147], v[52:53], v[166:167], v[146:147] op_sel_hi:[1,0,1]
	v_pk_fma_f32 v[148:149], v[54:55], v[166:167], v[148:149] op_sel_hi:[1,0,1]
	v_and_b32_e32 v158, 0xffff0000, v81
	v_pk_fma_f32 v[112:113], v[52:53], v[158:159], v[112:113] op_sel_hi:[1,0,1]
	v_pk_fma_f32 v[114:115], v[54:55], v[158:159], v[114:115] op_sel_hi:[1,0,1]
	v_and_b32_e32 v160, 0xffff0000, v85
	v_pk_fma_f32 v[116:117], v[52:53], v[160:161], v[116:117] op_sel_hi:[1,0,1]
	v_pk_fma_f32 v[118:119], v[54:55], v[160:161], v[118:119] op_sel_hi:[1,0,1]
	v_and_b32_e32 v162, 0xffff0000, v89
; DI float bf2f(bf16_t v) { return __uint_as_float(((unsigned)v) << 16); }
; DI void nsa_compress(const Params& p, int l, int item, char* smem) {
;     ...
;     for (int u = 0; u < 8; ++u) { const int i = i0 + ib + u, tk = i >> 6, d = i & 63; const float pv = pe[i]; const f32x4 w = wr[u];
;       bias[0] += pv * w[0]; bias[1] += pv * w[1]; bias[2] += pv * w[2]; bias[3] += pv * w[3];
; #pragma unroll
;       for (int r = 0; r < 8; ++r) { const float xv = bf2f(X[(16 * r + tk) * 64 + d]); acc[r][0] += xv * w[0]; acc[r][1] += xv * w[1]; acc[r][2] += xv * w[2]; acc[r][3] += xv * w[3]; } }
	v_pk_fma_f32 v[120:121], v[52:53], v[162:163], v[120:121] op_sel_hi:[1,0,1]
	v_pk_fma_f32 v[122:123], v[54:55], v[162:163], v[122:123] op_sel_hi:[1,0,1]
	v_and_b32_e32 v164, 0xffff0000, v93
	v_pk_fma_f32 v[124:125], v[52:53], v[164:165], v[124:125] op_sel_hi:[1,0,1]
	v_pk_fma_f32 v[126:127], v[54:55], v[164:165], v[126:127] op_sel_hi:[1,0,1]
	v_and_b32_e32 v158, 0xffff0000, v97
	v_pk_fma_f32 v[128:129], v[52:53], v[158:159], v[128:129] op_sel_hi:[1,0,1]
	v_pk_fma_f32 v[130:131], v[54:55], v[158:159], v[130:131] op_sel_hi:[1,0,1]
	v_and_b32_e32 v160, 0xffff0000, v101
	v_pk_fma_f32 v[132:133], v[52:53], v[160:161], v[132:133] op_sel_hi:[1,0,1]
	v_pk_fma_f32 v[134:135], v[54:55], v[160:161], v[134:135] op_sel_hi:[1,0,1]
	v_and_b32_e32 v162, 0xffff0000, v105
	v_pk_fma_f32 v[136:137], v[52:53], v[162:163], v[136:137] op_sel_hi:[1,0,1]
	v_pk_fma_f32 v[138:139], v[54:55], v[162:163], v[138:139] op_sel_hi:[1,0,1]
	v_and_b32_e32 v164, 0xffff0000, v109
	v_pk_fma_f32 v[72:73], v[52:53], v[164:165], v[72:73] op_sel_hi:[1,0,1]
	v_pk_fma_f32 v[74:75], v[54:55], v[164:165], v[74:75] op_sel_hi:[1,0,1]
	v_pk_fma_f32 v[146:147], v[56:57], v[220:221], v[146:147] op_sel_hi:[1,0,1]
	v_pk_fma_f32 v[148:149], v[58:59], v[220:221], v[148:149] op_sel_hi:[1,0,1]
	v_lshlrev_b32_e32 v158, 16, v82
	v_pk_fma_f32 v[112:113], v[56:57], v[158:159], v[112:113] op_sel_hi:[1,0,1]
	v_pk_fma_f32 v[114:115], v[58:59], v[158:159], v[114:115] op_sel_hi:[1,0,1]
	v_lshlrev_b32_e32 v160, 16, v86
	v_pk_fma_f32 v[116:117], v[56:57], v[160:161], v[116:117] op_sel_hi:[1,0,1]
	v_pk_fma_f32 v[118:119], v[58:59], v[160:161], v[118:119] op_sel_hi:[1,0,1]
	v_lshlrev_b32_e32 v162, 16, v90
	v_pk_fma_f32 v[120:121], v[56:57], v[162:163], v[120:121] op_sel_hi:[1,0,1]
	v_pk_fma_f32 v[122:123], v[58:59], v[162:163], v[122:123] op_sel_hi:[1,0,1]
	v_lshlrev_b32_e32 v164, 16, v94
	v_pk_fma_f32 v[124:125], v[56:57], v[164:165], v[124:125] op_sel_hi:[1,0,1]
	v_pk_fma_f32 v[126:127], v[58:59], v[164:165], v[126:127] op_sel_hi:[1,0,1]
	v_lshlrev_b32_e32 v158, 16, v98
	v_pk_fma_f32 v[128:129], v[56:57], v[158:159], v[128:129] op_sel_hi:[1,0,1]
	v_pk_fma_f32 v[130:131], v[58:59], v[158:159], v[130:131] op_sel_hi:[1,0,1]
	v_lshlrev_b32_e32 v160, 16, v102
	v_pk_fma_f32 v[132:133], v[56:57], v[160:161], v[132:133] op_sel_hi:[1,0,1]
	v_pk_fma_f32 v[134:135], v[58:59], v[160:161], v[134:135] op_sel_hi:[1,0,1]
	v_lshlrev_b32_e32 v162, 16, v106
	v_pk_fma_f32 v[136:137], v[56:57], v[162:163], v[136:137] op_sel_hi:[1,0,1]
	v_pk_fma_f32 v[138:139], v[58:59], v[162:163], v[138:139] op_sel_hi:[1,0,1]
	v_lshlrev_b32_e32 v164, 16, v110
	v_pk_fma_f32 v[72:73], v[56:57], v[164:165], v[72:73] op_sel_hi:[1,0,1]
	v_pk_fma_f32 v[74:75], v[58:59], v[164:165], v[74:75] op_sel_hi:[1,0,1]
	v_mov_b32_e32 v166, v221
	v_pk_fma_f32 v[146:147], v[60:61], v[166:167], v[146:147] op_sel_hi:[1,0,1]
	v_pk_fma_f32 v[148:149], v[62:63], v[166:167], v[148:149] op_sel_hi:[1,0,1]
	v_and_b32_e32 v158, 0xffff0000, v82
	v_pk_fma_f32 v[112:113], v[60:61], v[158:159], v[112:113] op_sel_hi:[1,0,1]
	v_pk_fma_f32 v[114:115], v[62:63], v[158:159], v[114:115] op_sel_hi:[1,0,1]
	v_and_b32_e32 v160, 0xffff0000, v86
	v_pk_fma_f32 v[116:117], v[60:61], v[160:161], v[116:117] op_sel_hi:[1,0,1]
	v_pk_fma_f32 v[118:119], v[62:63], v[160:161], v[118:119] op_sel_hi:[1,0,1]
	v_and_b32_e32 v162, 0xffff0000, v90
	v_pk_fma_f32 v[120:121], v[60:61], v[162:163], v[120:121] op_sel_hi:[1,0,1]
	v_pk_fma_f32 v[122:123], v[62:63], v[162:163], v[122:123] op_sel_hi:[1,0,1]
	v_and_b32_e32 v164, 0xffff0000, v94
	v_pk_fma_f32 v[124:125], v[60:61], v[164:165], v[124:125] op_sel_hi:[1,0,1]
	v_pk_fma_f32 v[126:127], v[62:63], v[164:165], v[126:127] op_sel_hi:[1,0,1]
	v_and_b32_e32 v158, 0xffff0000, v98
	v_pk_fma_f32 v[128:129], v[60:61], v[158:159], v[128:129] op_sel_hi:[1,0,1]
	v_pk_fma_f32 v[130:131], v[62:63], v[158:159], v[130:131] op_sel_hi:[1,0,1]
	v_and_b32_e32 v160, 0xffff0000, v102
	v_pk_fma_f32 v[132:133], v[60:61], v[160:161], v[132:133] op_sel_hi:[1,0,1]
	v_pk_fma_f32 v[134:135], v[62:63], v[160:161], v[134:135] op_sel_hi:[1,0,1]
	v_and_b32_e32 v162, 0xffff0000, v106
	v_pk_fma_f32 v[136:137], v[60:61], v[162:163], v[136:137] op_sel_hi:[1,0,1]
	v_pk_fma_f32 v[138:139], v[62:63], v[162:163], v[138:139] op_sel_hi:[1,0,1]
	v_and_b32_e32 v164, 0xffff0000, v110
	v_pk_fma_f32 v[72:73], v[60:61], v[164:165], v[72:73] op_sel_hi:[1,0,1]
	v_pk_fma_f32 v[74:75], v[62:63], v[164:165], v[74:75] op_sel_hi:[1,0,1]
	v_pk_fma_f32 v[146:147], v[64:65], v[222:223], v[146:147] op_sel_hi:[1,0,1]
	v_pk_fma_f32 v[148:149], v[66:67], v[222:223], v[148:149] op_sel_hi:[1,0,1]
	v_lshlrev_b32_e32 v158, 16, v83
	v_pk_fma_f32 v[112:113], v[64:65], v[158:159], v[112:113] op_sel_hi:[1,0,1]
	v_pk_fma_f32 v[114:115], v[66:67], v[158:159], v[114:115] op_sel_hi:[1,0,1]
	v_lshlrev_b32_e32 v160, 16, v87
	v_pk_fma_f32 v[116:117], v[64:65], v[160:161], v[116:117] op_sel_hi:[1,0,1]
	v_pk_fma_f32 v[118:119], v[66:67], v[160:161], v[118:119] op_sel_hi:[1,0,1]
	v_lshlrev_b32_e32 v162, 16, v91
	v_pk_fma_f32 v[120:121], v[64:65], v[162:163], v[120:121] op_sel_hi:[1,0,1]
	v_pk_fma_f32 v[122:123], v[66:67], v[162:163], v[122:123] op_sel_hi:[1,0,1]
	v_lshlrev_b32_e32 v164, 16, v95
	v_pk_fma_f32 v[124:125], v[64:65], v[164:165], v[124:125] op_sel_hi:[1,0,1]
	v_pk_fma_f32 v[126:127], v[66:67], v[164:165], v[126:127] op_sel_hi:[1,0,1]
	v_lshlrev_b32_e32 v158, 16, v99
	v_pk_fma_f32 v[128:129], v[64:65], v[158:159], v[128:129] op_sel_hi:[1,0,1]
	v_pk_fma_f32 v[130:131], v[66:67], v[158:159], v[130:131] op_sel_hi:[1,0,1]
	v_lshlrev_b32_e32 v160, 16, v103
	v_pk_fma_f32 v[132:133], v[64:65], v[160:161], v[132:133] op_sel_hi:[1,0,1]
; DI float bf2f(bf16_t v) { return __uint_as_float(((unsigned)v) << 16); }
; DI void nsa_compress(const Params& p, int l, int item, char* smem) {
;     ...
;     for (int u = 0; u < 8; ++u) { const int i = i0 + ib + u, tk = i >> 6, d = i & 63; const float pv = pe[i]; const f32x4 w = wr[u];
;       bias[0] += pv * w[0]; bias[1] += pv * w[1]; bias[2] += pv * w[2]; bias[3] += pv * w[3];
; #pragma unroll
;       for (int r = 0; r < 8; ++r) { const float xv = bf2f(X[(16 * r + tk) * 64 + d]); acc[r][0] += xv * w[0]; acc[r][1] += xv * w[1]; acc[r][2] += xv * w[2]; acc[r][3] += xv * w[3]; } }
;   }
; #pragma unroll
;   for (int r = 0; r < 8; ++r) *(float4*)(Hp + (wv * 8 + r) * 256 + lane * 4) = (float4){acc[r][0] + bias[0], acc[r][1] + bias[1], acc[r][2] + bias[2], acc[r][3] + bias[3]};
	v_pk_fma_f32 v[134:135], v[66:67], v[160:161], v[134:135] op_sel_hi:[1,0,1]
	v_lshlrev_b32_e32 v162, 16, v107
	v_pk_fma_f32 v[136:137], v[64:65], v[162:163], v[136:137] op_sel_hi:[1,0,1]
	v_pk_fma_f32 v[138:139], v[66:67], v[162:163], v[138:139] op_sel_hi:[1,0,1]
	v_lshlrev_b32_e32 v164, 16, v111
	v_pk_fma_f32 v[72:73], v[64:65], v[164:165], v[72:73] op_sel_hi:[1,0,1]
	v_pk_fma_f32 v[74:75], v[66:67], v[164:165], v[74:75] op_sel_hi:[1,0,1]
	v_mov_b32_e32 v166, v223
	v_pk_fma_f32 v[146:147], v[68:69], v[166:167], v[146:147] op_sel_hi:[1,0,1]
	v_pk_fma_f32 v[148:149], v[70:71], v[166:167], v[148:149] op_sel_hi:[1,0,1]
	v_and_b32_e32 v158, 0xffff0000, v83
	v_pk_fma_f32 v[112:113], v[68:69], v[158:159], v[112:113] op_sel_hi:[1,0,1]
	v_pk_fma_f32 v[114:115], v[70:71], v[158:159], v[114:115] op_sel_hi:[1,0,1]
	v_and_b32_e32 v160, 0xffff0000, v87
	v_pk_fma_f32 v[116:117], v[68:69], v[160:161], v[116:117] op_sel_hi:[1,0,1]
	v_pk_fma_f32 v[118:119], v[70:71], v[160:161], v[118:119] op_sel_hi:[1,0,1]
	v_and_b32_e32 v162, 0xffff0000, v91
	v_pk_fma_f32 v[120:121], v[68:69], v[162:163], v[120:121] op_sel_hi:[1,0,1]
	v_pk_fma_f32 v[122:123], v[70:71], v[162:163], v[122:123] op_sel_hi:[1,0,1]
	v_and_b32_e32 v164, 0xffff0000, v95
	v_pk_fma_f32 v[124:125], v[68:69], v[164:165], v[124:125] op_sel_hi:[1,0,1]
	v_pk_fma_f32 v[126:127], v[70:71], v[164:165], v[126:127] op_sel_hi:[1,0,1]
	v_and_b32_e32 v158, 0xffff0000, v99
	v_pk_fma_f32 v[128:129], v[68:69], v[158:159], v[128:129] op_sel_hi:[1,0,1]
	v_pk_fma_f32 v[130:131], v[70:71], v[158:159], v[130:131] op_sel_hi:[1,0,1]
	v_and_b32_e32 v160, 0xffff0000, v103
	v_pk_fma_f32 v[132:133], v[68:69], v[160:161], v[132:133] op_sel_hi:[1,0,1]
	v_pk_fma_f32 v[134:135], v[70:71], v[160:161], v[134:135] op_sel_hi:[1,0,1]
	v_and_b32_e32 v162, 0xffff0000, v107
	v_pk_fma_f32 v[136:137], v[68:69], v[162:163], v[136:137] op_sel_hi:[1,0,1]
	v_pk_fma_f32 v[138:139], v[70:71], v[162:163], v[138:139] op_sel_hi:[1,0,1]
	v_and_b32_e32 v164, 0xffff0000, v111
	v_pk_fma_f32 v[72:73], v[68:69], v[164:165], v[72:73] op_sel_hi:[1,0,1]
	v_pk_fma_f32 v[74:75], v[70:71], v[164:165], v[74:75] op_sel_hi:[1,0,1]
	v_lshlrev_b32_e32 v0, 2, v32
	v_lshl_or_b32 v4, v78, 13, v0
	v_pk_add_f32 v[0:1], v[146:147], v[112:113]
	v_pk_add_f32 v[2:3], v[148:149], v[114:115]
	ds_write_b128 v4, v[0:3] offset:18432
	v_pk_add_f32 v[0:1], v[146:147], v[116:117]
	v_pk_add_f32 v[2:3], v[148:149], v[118:119]
	ds_write_b128 v4, v[0:3] offset:19456
	v_pk_add_f32 v[0:1], v[146:147], v[120:121]
	v_pk_add_f32 v[2:3], v[148:149], v[122:123]
	ds_write_b128 v4, v[0:3] offset:20480
	v_pk_add_f32 v[0:1], v[146:147], v[124:125]
	v_pk_add_f32 v[2:3], v[148:149], v[126:127]
	ds_write_b128 v4, v[0:3] offset:21504
	v_pk_add_f32 v[0:1], v[146:147], v[128:129]
	v_pk_add_f32 v[2:3], v[148:149], v[130:131]
	ds_write_b128 v4, v[0:3] offset:22528
	v_pk_add_f32 v[0:1], v[146:147], v[132:133]
	v_pk_add_f32 v[2:3], v[148:149], v[134:135]
	ds_write_b128 v4, v[0:3] offset:23552
	v_pk_add_f32 v[0:1], v[146:147], v[136:137]
	v_pk_add_f32 v[2:3], v[148:149], v[138:139]
	ds_write_b128 v4, v[0:3] offset:24576
	v_pk_add_f32 v[0:1], v[146:147], v[72:73]
	v_pk_add_f32 v[2:3], v[148:149], v[74:75]
	ds_write_b128 v4, v[0:3] offset:25600
	v_lshlrev_b32_e32 v0, 2, v33
	s_waitcnt lgkmcnt(0)
	s_barrier
; DI void nsa_compress(const Params& p, int l, int item, char* smem) {
;     ...
;   __syncthreads();
; #pragma unroll
;   for (int q = 0; q < 8; ++q) { const int idx = tid + 256 * q; const float hv = Hp[idx] + Hp[2048 + idx] + Hp[4096 + idx] + Hp[6144 + idx]; Hp[idx] = hv / (1.f + __expf(-hv)); }
;   __syncthreads();
;   const float* H = Hp;
;   const float* w2 = (kv ? p.cvw2 : p.ckw2) + (size_t)l * 256 * 64;
;   const int r0 = tid >> 6, d = tid & 63; float o0 = 0.f, o1 = 0.f;
	ds_read2st64_b32 v[2:3], v0 offset0:72 offset1:76
	ds_read2st64_b32 v[4:5], v0 offset0:104 offset1:108
	ds_read2st64_b32 v[6:7], v0 offset0:136 offset1:140
	ds_read2st64_b32 v[8:9], v0 offset0:168 offset1:172
	v_readlane_b32 s36, v245, 12
	s_and_b64 s[6:7], s[4:5], exec
	s_waitcnt lgkmcnt(2)
	v_add_f32_e32 v1, v2, v4
	s_waitcnt lgkmcnt(1)
	v_add_f32_e32 v1, v1, v6
	s_waitcnt lgkmcnt(0)
	v_add_f32_e32 v1, v1, v8
	v_mul_f32_e32 v2, 0xbfb8aa3b, v1
	v_exp_f32_e32 v2, v2
	v_readlane_b32 s38, v245, 14
	v_readlane_b32 s42, v245, 18
	v_readlane_b32 s39, v245, 15
	v_add_f32_e32 v2, 1.0, v2
	v_div_scale_f32 v4, s[6:7], v2, v2, v1
	v_rcp_f32_e32 v6, v4
	v_readlane_b32 s43, v245, 19
	v_readlane_b32 s12, v242, 30
	s_cselect_b32 s2, s39, s43
	v_fma_f32 v8, -v4, v6, 1.0
	v_fmac_f32_e32 v6, v8, v6
	v_div_scale_f32 v8, vcc, v1, v2, v1
	v_mul_f32_e32 v10, v8, v6
	v_fma_f32 v11, -v4, v10, v8
	v_fmac_f32_e32 v10, v11, v6
	v_fma_f32 v4, -v4, v10, v8
	v_div_fmas_f32 v4, v4, v6, v10
	v_div_fixup_f32 v1, v4, v2, v1
	v_add_f32_e32 v2, v3, v5
	v_add_f32_e32 v2, v2, v7
	v_add_f32_e32 v2, v2, v9
	v_mul_f32_e32 v3, 0xbfb8aa3b, v2
	v_exp_f32_e32 v3, v3
	v_readlane_b32 s13, v242, 31
	v_mov_b32_e32 v33, v143
	s_mov_b64 s[20:21], 0x400
	v_add_f32_e32 v3, 1.0, v3
	v_div_scale_f32 v4, s[6:7], v3, v3, v2
	v_rcp_f32_e32 v5, v4
	s_mov_b64 s[22:23], 0x800
	s_mov_b64 s[24:25], 0xc00
	s_mov_b64 s[14:15], 0x200
	v_fma_f32 v6, -v4, v5, 1.0
	v_fmac_f32_e32 v5, v6, v5
	v_div_scale_f32 v6, vcc, v2, v3, v2
	v_mul_f32_e32 v7, v6, v5
	v_fma_f32 v8, -v4, v7, v6
	v_fmac_f32_e32 v7, v8, v5
	v_fma_f32 v4, -v4, v7, v6
	v_div_fmas_f32 v4, v4, v5, v7
	v_div_fixup_f32 v2, v4, v3, v2
	ds_write2st64_b32 v0, v1, v2 offset0:72 offset1:76
	ds_read2st64_b32 v[2:3], v0 offset0:80 offset1:84
	ds_read2st64_b32 v[4:5], v0 offset0:112 offset1:116
	ds_read2st64_b32 v[6:7], v0 offset0:144 offset1:148
	ds_read2st64_b32 v[8:9], v0 offset0:176 offset1:180
	s_mov_b64 s[30:31], 0x300
	v_readlane_b32 s37, v245, 13
	s_waitcnt lgkmcnt(2)
	v_add_f32_e32 v1, v2, v4
	s_waitcnt lgkmcnt(1)
	v_add_f32_e32 v1, v1, v6
	s_waitcnt lgkmcnt(0)
	v_add_f32_e32 v1, v1, v8
	v_mul_f32_e32 v2, 0xbfb8aa3b, v1
	v_exp_f32_e32 v2, v2
	v_readlane_b32 s40, v245, 16
	v_readlane_b32 s41, v245, 17
	v_add_f32_e32 v2, 1.0, v2
	v_div_scale_f32 v4, s[6:7], v2, v2, v1
	v_rcp_f32_e32 v6, v4
	s_nop 0
	v_fma_f32 v8, -v4, v6, 1.0
	v_fmac_f32_e32 v6, v8, v6
	v_div_scale_f32 v8, vcc, v1, v2, v1
	v_mul_f32_e32 v10, v8, v6
	v_fma_f32 v11, -v4, v10, v8
	v_fmac_f32_e32 v10, v11, v6
	v_fma_f32 v4, -v4, v10, v8
	v_div_fmas_f32 v4, v4, v6, v10
	v_div_fixup_f32 v1, v4, v2, v1
	v_add_f32_e32 v2, v3, v5
	v_add_f32_e32 v2, v2, v7
	v_add_f32_e32 v2, v2, v9
	v_mul_f32_e32 v3, 0xbfb8aa3b, v2
	v_exp_f32_e32 v3, v3
	s_nop 0
	v_add_f32_e32 v3, 1.0, v3
	v_div_scale_f32 v4, s[6:7], v3, v3, v2
	v_rcp_f32_e32 v5, v4
	s_nop 0
	v_fma_f32 v6, -v4, v5, 1.0
	v_fmac_f32_e32 v5, v6, v5
	v_div_scale_f32 v6, vcc, v2, v3, v2
	v_mul_f32_e32 v7, v6, v5
	v_fma_f32 v8, -v4, v7, v6
	v_fmac_f32_e32 v7, v8, v5
	v_fma_f32 v4, -v4, v7, v6
	v_div_fmas_f32 v4, v4, v5, v7
	v_div_fixup_f32 v2, v4, v3, v2
	ds_write2st64_b32 v0, v1, v2 offset0:80 offset1:84
	ds_read2st64_b32 v[2:3], v0 offset0:88 offset1:92
	ds_read2st64_b32 v[4:5], v0 offset0:120 offset1:124
	ds_read2st64_b32 v[6:7], v0 offset0:152 offset1:156
	ds_read2st64_b32 v[8:9], v0 offset0:184 offset1:188
	s_waitcnt lgkmcnt(2)
	v_add_f32_e32 v1, v2, v4
	s_waitcnt lgkmcnt(1)
	v_add_f32_e32 v1, v1, v6
	s_waitcnt lgkmcnt(0)
	v_add_f32_e32 v1, v1, v8
	v_mul_f32_e32 v2, 0xbfb8aa3b, v1
	v_exp_f32_e32 v2, v2
	s_nop 0
	v_add_f32_e32 v2, 1.0, v2
	v_div_scale_f32 v4, s[6:7], v2, v2, v1
	v_rcp_f32_e32 v6, v4
	s_nop 0
	v_fma_f32 v8, -v4, v6, 1.0
	v_fmac_f32_e32 v6, v8, v6
	v_div_scale_f32 v8, vcc, v1, v2, v1
	v_mul_f32_e32 v10, v8, v6
	v_fma_f32 v11, -v4, v10, v8
	v_fmac_f32_e32 v10, v11, v6
	v_fma_f32 v4, -v4, v10, v8
	v_div_fmas_f32 v4, v4, v6, v10
	v_div_fixup_f32 v1, v4, v2, v1
	v_add_f32_e32 v2, v3, v5
	v_add_f32_e32 v2, v2, v7
	v_add_f32_e32 v2, v2, v9
	v_mul_f32_e32 v3, 0xbfb8aa3b, v2
	v_exp_f32_e32 v3, v3
	s_nop 0
	v_add_f32_e32 v3, 1.0, v3
	v_div_scale_f32 v4, s[6:7], v3, v3, v2
	v_rcp_f32_e32 v5, v4
	s_nop 0
	v_fma_f32 v6, -v4, v5, 1.0
	v_fmac_f32_e32 v5, v6, v5
	v_div_scale_f32 v6, vcc, v2, v3, v2
	v_mul_f32_e32 v7, v6, v5
	v_fma_f32 v8, -v4, v7, v6
	v_fmac_f32_e32 v7, v8, v5
	v_fma_f32 v4, -v4, v7, v6
	v_div_fmas_f32 v4, v4, v5, v7
	v_div_fixup_f32 v2, v4, v3, v2
	ds_write2st64_b32 v0, v1, v2 offset0:88 offset1:92
	ds_read2st64_b32 v[2:3], v0 offset0:96 offset1:100
	ds_read2st64_b32 v[4:5], v0 offset0:128 offset1:132
	ds_read2st64_b32 v[6:7], v0 offset0:160 offset1:164
	ds_read2st64_b32 v[8:9], v0 offset0:192 offset1:196
	s_waitcnt lgkmcnt(2)
	v_add_f32_e32 v1, v2, v4
	s_waitcnt lgkmcnt(1)
	v_add_f32_e32 v1, v1, v6
	s_waitcnt lgkmcnt(0)
	v_add_f32_e32 v1, v1, v8
	v_mul_f32_e32 v2, 0xbfb8aa3b, v1
	v_exp_f32_e32 v2, v2
	s_nop 0
	v_add_f32_e32 v2, 1.0, v2
	v_div_scale_f32 v4, s[6:7], v2, v2, v1
	v_rcp_f32_e32 v6, v4
	s_nop 0
	v_fma_f32 v8, -v4, v6, 1.0
	v_fmac_f32_e32 v6, v8, v6
	v_div_scale_f32 v8, vcc, v1, v2, v1
	v_mul_f32_e32 v10, v8, v6
	v_fma_f32 v11, -v4, v10, v8
	v_fmac_f32_e32 v10, v11, v6
	v_fma_f32 v4, -v4, v10, v8
	v_div_fmas_f32 v4, v4, v6, v10
	v_div_fixup_f32 v1, v4, v2, v1
	v_add_f32_e32 v2, v3, v5
	v_add_f32_e32 v2, v2, v7
	v_add_f32_e32 v2, v2, v9
	v_mul_f32_e32 v3, 0xbfb8aa3b, v2
	v_exp_f32_e32 v3, v3
	s_nop 0
	v_add_f32_e32 v3, 1.0, v3
	v_div_scale_f32 v4, s[6:7], v3, v3, v2
	v_rcp_f32_e32 v5, v4
	s_cselect_b32 s6, s38, s42
	s_add_u32 s6, s6, s12
	s_addc_u32 s7, s2, s13
	v_fma_f32 v6, -v4, v5, 1.0
	v_fmac_f32_e32 v5, v6, v5
	v_div_scale_f32 v6, vcc, v2, v3, v2
	v_mul_f32_e32 v7, v6, v5
	v_fma_f32 v8, -v4, v7, v6
	v_fmac_f32_e32 v7, v8, v5
	v_fma_f32 v4, -v4, v7, v6
	v_div_fmas_f32 v4, v4, v5, v7
	v_div_fixup_f32 v2, v4, v3, v2
	ds_write2st64_b32 v0, v1, v2 offset0:96 offset1:100
	v_mov_b32_e32 v0, 0
	v_lshl_add_u64 v[2:3], s[6:7], 0, v[32:33]
	v_lshl_add_u32 v4, v78, 10, v193
	s_mov_b32 s2, -16
	v_mov_b32_e32 v1, v0
	s_mov_b64 s[12:13], 0x1000
	s_waitcnt lgkmcnt(0)
	s_barrier

; DI int tid_() { int t = __builtin_amdgcn_workitem_id_x(); asm volatile("" : "+v"(t)); return t; }
; DI int q_pop(unsigned* ctr, char* smem) {
;   int* sh = (int*)(smem + 65024);
;   __syncthreads();
;   if (tid_() == 0) *sh = (int)atomicAdd(ctr, 1u);
;   __syncthreads();
;   return *sh;
; }
;   unsigned* ctr = (unsigned*)(p.ws + OFF_CNT) + cslot;
;   const int total = 32 + 64 * 24 + 256;
;   bool first = true;
;   for (;;) {
;     const int it = (first ? (int)blockIdx.x : q_pop(ctr, smem) + (int)gridDim.x) + skip; first = false;
;     if (it >= total) break;
.LBB0_566:
	v_mov_b32_e32 v0, v170
	s_waitcnt lgkmcnt(0)
	s_barrier
	s_nop 0
	v_cmp_eq_u32_e32 vcc, 0, v0
	s_and_saveexec_b64 s[0:1], vcc
	s_xor_b64 s[0:1], exec, s[0:1]
	s_cbranch_execz .LBB0_499
	s_mov_b64 s[6:7], exec
	v_mbcnt_lo_u32_b32 v0, s6, 0
	v_mbcnt_hi_u32_b32 v0, s7, v0
	v_cmp_eq_u32_e32 vcc, 0, v0
	s_and_saveexec_b64 s[4:5], vcc
	s_cbranch_execz .LBB0_498
	s_bcnt1_i32_b64 s2, s[6:7]
	v_readlane_b32 s6, v244, 25
	v_mov_b32_e32 v1, s2
	v_readlane_b32 s7, v244, 26
	v_readlane_b32 s2, v242, 62
	s_lshl_b32 s2, s2, 5
	s_add_u32 s6, s6, s2
	s_addc_u32 s7, s7, 0
	s_nop 4
	global_atomic_add v1, v143, v1, s[6:7] sc0
	s_branch .LBB0_498
.LBB0_569:
	v_readlane_b32 s0, v242, 62
	s_cmp_eq_u32 s0, 1
	s_cbranch_scc1 .Lm2_enter
	s_mov_b64 s[0:1], 0
